# the 12 remaining provably redundant s_waitcnt lgkmcnt(0) deleted (10 in prologue / H loops with nothing outstanding since the previous drain, 2 at the head of DOWN's K-loop body and its peeled copy);
# speedup vs baseline: 1.0062x; 1.0016x over previous
; #define LAS __attribute__((address_space(3)))
; template <bool WITH_SW, bool TILED = false> __device__ __forceinline__ void wt_col_item(const float* W, int N, bf16_t* WT, int Kst, int kb0, int kb1, bool upmap, LAS float* scr, int nb, int lane, const float* shift, float* SWo) {
;     ...
;     for (int kb = kb0; kb < kb1; ++kb) { const int k0 = 64 * kb;
; #pragma unroll
;         for (int i = 0; i < 8; ++i) { LAS float* d = scr + ((lane >> 3) + 8 * i) * 33 + 4 * (lane & 7); d[0] = t[i].x; d[1] = t[i].y; d[2] = t[i].z; d[3] = t[i].w; }
;         if (kb + 1 < kb1) {
; #pragma unroll
;             for (int i = 0; i < 8; ++i) t[i] = __builtin_nontemporal_load((const f32x4*)(W + (size_t)(k0 + 64 + (lane >> 3) + 8 * i) * N + n0 + 4 * (lane & 7))); }
;         f32x4 s0[NB], s1[NB];
;         if constexpr (WITH_SW) {
; #pragma unroll
;             for (int b = 0; b < NB; ++b) { s0[b] = *(const f32x4*)(shift + (size_t)b * 6 * D + k0 + 8 * c); s1[b] = *(const f32x4*)(shift + (size_t)b * 6 * D + k0 + 8 * c + 4); } }
;         asm volatile("s_waitcnt lgkmcnt(0)" ::: "memory");
; #pragma unroll
;         for (int j = 0; j < 4; ++j) { const int n = (lane >> 3) + 8 * j; const LAS float* sp = scr + (8 * c) * 33 + n;
;             u32x4 o; o.x = cvt_pk_bf16_c(sp[0 * 33], sp[1 * 33]); o.y = cvt_pk_bf16_c(sp[2 * 33], sp[3 * 33]); o.z = cvt_pk_bf16_c(sp[4 * 33], sp[5 * 33]); o.w = cvt_pk_bf16_c(sp[6 * 33], sp[7 * 33]);
;             if constexpr (TILED) __builtin_nontemporal_store(o, (u32x4*)(WT + (size_t)((r0 + n) >> 8) * ((size_t)256 * Kst) + (size_t)(k0 >> 6) * (256 * 64) + ((r0 + n) & 255) * 64 + 8 * c));
;             else *(u32x4*)(WT + (size_t)(r0 + n) * Kst + k0 + 8 * c) = o;
;             if constexpr (WITH_SW) { float wv[8]; unpack8(o, wv);
; #pragma unroll
;                 for (int b = 0; b < NB; ++b) a[j][b] += (s0[b].x * wv[0] + s0[b].y * wv[1]) + (s0[b].z * wv[2] + s0[b].w * wv[3]) + (s1[b].x * wv[4] + s1[b].y * wv[5]) + (s1[b].z * wv[6] + s1[b].w * wv[7]); } }
;         asm volatile("s_waitcnt lgkmcnt(0)" ::: "memory");
; __device__ __forceinline__ void pro_a(LAS unsigned char* lds, const float* const* in, unsigned char* wsl, int cid, int G, int tid) {
;     ...
;         for (int it = cid * 8 + wave; it < L * (I_OUT + I_DN); it += G * 8) { const int l = it / (I_OUT + I_DN), r = it % (I_OUT + I_DN);
.LBB0_23:
	s_add_i32 s12, s16, s12
	s_lshl_b64 s[14:15], s[14:15], 1
	s_waitcnt vmcnt(11)
	ds_write2_b32 v43, v0, v1 offset1:1
	ds_write2_b32 v43, v2, v3 offset0:2 offset1:3
	s_waitcnt vmcnt(10)
	ds_write2_b32 v45, v4, v5 offset1:1
	ds_write2_b32 v47, v6, v7 offset1:1
	s_waitcnt vmcnt(9)
	ds_write2_b32 v87, v8, v9 offset1:1
	ds_write2_b32 v88, v10, v11 offset1:1
	s_waitcnt vmcnt(8)
	ds_write2_b32 v89, v12, v13 offset1:1
	ds_write2_b32 v90, v14, v15 offset1:1
	s_waitcnt vmcnt(7)
	ds_write2_b32 v91, v16, v17 offset1:1
	ds_write2_b32 v92, v18, v19 offset1:1
	s_waitcnt vmcnt(6)
	ds_write2_b32 v93, v20, v21 offset1:1
	ds_write2_b32 v94, v22, v23 offset1:1
	s_waitcnt vmcnt(5)
	ds_write2_b32 v95, v24, v25 offset1:1
	ds_write2_b32 v96, v26, v27 offset1:1
	s_waitcnt vmcnt(4)
	ds_write2_b32 v97, v28, v29 offset1:1
	ds_write2_b32 v98, v30, v31 offset1:1
	s_add_u32 s13, s3, s14
	s_waitcnt lgkmcnt(0)
	s_addc_u32 s15, s24, s15
	ds_read2_b32 v[4:5], v74 offset0:33 offset1:41
	ds_read2_b32 v[6:7], v74 offset1:8
	ds_read2_b32 v[8:9], v74 offset0:66 offset1:74
	ds_read2_b32 v[10:11], v74 offset0:99 offset1:107
	ds_read2_b32 v[12:13], v74 offset0:132 offset1:140
	ds_read2_b32 v[14:15], v74 offset0:165 offset1:173
	ds_read2_b32 v[16:17], v74 offset0:198 offset1:206
	ds_read2_b32 v[18:19], v74 offset0:231 offset1:239
	s_add_u32 s14, s13, s18
	s_addc_u32 s15, s15, s19
	v_mov_b32_e32 v41, v35
	s_ashr_i32 s13, s12, 31
	v_lshl_add_u64 v[48:49], s[14:15], 0, v[40:41]
	v_or_b32_e32 v41, s0, v72
	s_lshl_b64 s[12:13], s[12:13], 15
	v_lshl_add_u64 v[20:21], v[48:49], 0, s[12:13]
	v_lshlrev_b32_e32 v22, 7, v41
	v_mov_b32_e32 v23, v35
	s_waitcnt lgkmcnt(6)
	v_cvt_pk_bf16_f32 v0, v6, v4
	s_waitcnt lgkmcnt(4)
	v_cvt_pk_bf16_f32 v1, v8, v10
	s_waitcnt lgkmcnt(2)
	v_cvt_pk_bf16_f32 v2, v12, v14
	s_waitcnt lgkmcnt(0)
	v_cvt_pk_bf16_f32 v3, v16, v18
	v_lshl_add_u64 v[22:23], v[20:21], 0, v[22:23]
	global_store_dwordx4 v[22:23], v[0:3], off nt
	v_mov_b32_e32 v47, v35
	v_mov_b32_e32 v45, v35
	v_cvt_pk_bf16_f32 v0, v7, v5
	v_cvt_pk_bf16_f32 v1, v9, v11
	v_cvt_pk_bf16_f32 v2, v13, v15
	v_cvt_pk_bf16_f32 v3, v17, v19
	ds_read2_b32 v[6:7], v74 offset0:49 offset1:57
	ds_read2_b32 v[8:9], v74 offset0:16 offset1:24
	ds_read2_b32 v[10:11], v74 offset0:82 offset1:90
	ds_read2_b32 v[12:13], v74 offset0:115 offset1:123
	ds_read2_b32 v[14:15], v74 offset0:148 offset1:156
	ds_read2_b32 v[16:17], v74 offset0:181 offset1:189
	ds_read2_b32 v[18:19], v74 offset0:214 offset1:222
	ds_read2_b32 v[22:23], v74 offset0:247 offset1:255
	v_lshl_add_u64 v[4:5], v[20:21], 0, v[46:47]
	global_store_dwordx4 v[4:5], v[0:3], off nt
	v_lshl_add_u64 v[4:5], v[20:21], 0, v[44:45]
	v_mov_b32_e32 v43, v35
	s_waitcnt lgkmcnt(6)
	v_cvt_pk_bf16_f32 v0, v8, v6
	s_waitcnt lgkmcnt(4)
	v_cvt_pk_bf16_f32 v1, v10, v12
	s_waitcnt lgkmcnt(2)
	v_cvt_pk_bf16_f32 v2, v14, v16
	s_waitcnt lgkmcnt(0)
	v_cvt_pk_bf16_f32 v3, v18, v22
	global_store_dwordx4 v[4:5], v[0:3], off nt
	v_lshl_add_u64 v[4:5], v[20:21], 0, v[42:43]
	s_nop 0
	v_cvt_pk_bf16_f32 v0, v9, v7
	v_cvt_pk_bf16_f32 v1, v11, v13
	v_cvt_pk_bf16_f32 v2, v15, v17
	v_cvt_pk_bf16_f32 v3, v19, v23
	global_store_dwordx4 v[4:5], v[0:3], off nt
.LBB0_24:
	s_add_i32 s2, s2, s25
	s_cmpk_gt_i32 s2, 0xeff
	s_cbranch_scc1 .LBB0_36

; __device__ __forceinline__ unsigned cvt_pk_bf16_c(float lo, float hi) { const f32x2_t v = {lo, hi}; return __builtin_bit_cast(unsigned, __builtin_convertvector(v, bf16x2_t)); }
; #define LAS __attribute__((address_space(3)))
; template <bool WITH_SW, bool TILED = false> __device__ __forceinline__ void wt_col_item(const float* W, int N, bf16_t* WT, int Kst, int kb0, int kb1, bool upmap, LAS float* scr, int nb, int lane, const float* shift, float* SWo) {
;     ...
;         asm volatile("s_waitcnt lgkmcnt(0)" ::: "memory");
; #pragma unroll
;         for (int j = 0; j < 4; ++j) { const int n = (lane >> 3) + 8 * j; const LAS float* sp = scr + (8 * c) * 33 + n;
;             u32x4 o; o.x = cvt_pk_bf16_c(sp[0 * 33], sp[1 * 33]); o.y = cvt_pk_bf16_c(sp[2 * 33], sp[3 * 33]); o.z = cvt_pk_bf16_c(sp[4 * 33], sp[5 * 33]); o.w = cvt_pk_bf16_c(sp[6 * 33], sp[7 * 33]);
;             if constexpr (TILED) __builtin_nontemporal_store(o, (u32x4*)(WT + (size_t)((r0 + n) >> 8) * ((size_t)256 * Kst) + (size_t)(k0 >> 6) * (256 * 64) + ((r0 + n) & 255) * 64 + 8 * c));
;             else *(u32x4*)(WT + (size_t)(r0 + n) * Kst + k0 + 8 * c) = o;
;             if constexpr (WITH_SW) { float wv[8]; unpack8(o, wv);
; #pragma unroll
;                 for (int b = 0; b < NB; ++b) a[j][b] += (s0[b].x * wv[0] + s0[b].y * wv[1]) + (s0[b].z * wv[2] + s0[b].w * wv[3]) + (s1[b].x * wv[4] + s1[b].y * wv[5]) + (s1[b].z * wv[6] + s1[b].w * wv[7]); } }
;         asm volatile("s_waitcnt lgkmcnt(0)" ::: "memory");
.LBB0_28:
	s_waitcnt lgkmcnt(0)
	ds_read2_b32 v[58:59], v74 offset0:33 offset1:41
	ds_read2_b32 v[60:61], v74 offset1:8
	ds_read2_b32 v[62:63], v74 offset0:66 offset1:74
	ds_read2_b32 v[64:65], v74 offset0:99 offset1:107
	ds_read2_b32 v[66:67], v74 offset0:132 offset1:140
	ds_read2_b32 v[68:69], v74 offset0:165 offset1:173
	ds_read2_b32 v[70:71], v74 offset0:198 offset1:206
	ds_read2_b32 v[88:89], v74 offset0:231 offset1:239
	s_waitcnt lgkmcnt(6)
	v_cvt_pk_bf16_f32 v54, v60, v58
	s_waitcnt lgkmcnt(4)
	v_cvt_pk_bf16_f32 v55, v62, v64
	s_waitcnt lgkmcnt(2)
	v_cvt_pk_bf16_f32 v56, v66, v68
	v_lshl_add_u64 v[90:91], v[46:47], 0, v[44:45]
	s_waitcnt lgkmcnt(0)
	v_cvt_pk_bf16_f32 v57, v70, v88
	global_store_dwordx4 v[90:91], v[54:57], off nt
	s_add_i32 s15, s15, 64
	s_add_i32 s0, s0, 1
	v_cvt_pk_bf16_f32 v54, v61, v59
	v_cvt_pk_bf16_f32 v55, v63, v65
	v_cvt_pk_bf16_f32 v56, v67, v69
	v_cvt_pk_bf16_f32 v57, v71, v89
	ds_read2_b32 v[60:61], v74 offset0:49 offset1:57
	ds_read2_b32 v[62:63], v74 offset0:16 offset1:24
	ds_read2_b32 v[64:65], v74 offset0:82 offset1:90
	ds_read2_b32 v[66:67], v74 offset0:115 offset1:123
	ds_read2_b32 v[68:69], v74 offset0:148 offset1:156
	ds_read2_b32 v[70:71], v74 offset0:181 offset1:189
	ds_read2_b32 v[88:89], v74 offset0:214 offset1:222
	ds_read2_b32 v[90:91], v74 offset0:247 offset1:255
	v_lshl_add_u64 v[58:59], v[46:47], 0, v[48:49]
	global_store_dwordx4 v[58:59], v[54:57], off nt
	v_lshl_add_u64 v[58:59], v[46:47], 0, v[50:51]
	s_cmpk_eq_i32 s15, 0x200
	s_waitcnt lgkmcnt(6)
	v_cvt_pk_bf16_f32 v54, v62, v60
	s_waitcnt lgkmcnt(4)
	v_cvt_pk_bf16_f32 v55, v64, v66
	s_waitcnt lgkmcnt(2)
	v_cvt_pk_bf16_f32 v56, v68, v70
	s_waitcnt lgkmcnt(0)
	v_cvt_pk_bf16_f32 v57, v88, v90
	global_store_dwordx4 v[58:59], v[54:57], off nt
	v_lshl_add_u64 v[58:59], v[46:47], 0, v[52:53]
	v_lshl_add_u64 v[46:47], v[46:47], 0, s[10:11]
	v_cvt_pk_bf16_f32 v54, v63, v61
	v_cvt_pk_bf16_f32 v55, v65, v67
	v_cvt_pk_bf16_f32 v56, v69, v71
	v_cvt_pk_bf16_f32 v57, v89, v91
	global_store_dwordx4 v[58:59], v[54:57], off nt
	s_cbranch_scc1 .LBB0_31

; __device__ __forceinline__ unsigned cvt_pk_bf16_c(float lo, float hi) { const f32x2_t v = {lo, hi}; return __builtin_bit_cast(unsigned, __builtin_convertvector(v, bf16x2_t)); }
; #define LAS __attribute__((address_space(3)))
; template <bool WITH_SW, bool TILED = false> __device__ __forceinline__ void wt_col_item(const float* W, int N, bf16_t* WT, int Kst, int kb0, int kb1, bool upmap, LAS float* scr, int nb, int lane, const float* shift, float* SWo) {
;     ...
;     for (int kb = kb0; kb < kb1; ++kb) { const int k0 = 64 * kb;
; #pragma unroll
;         for (int i = 0; i < 8; ++i) { LAS float* d = scr + ((lane >> 3) + 8 * i) * 33 + 4 * (lane & 7); d[0] = t[i].x; d[1] = t[i].y; d[2] = t[i].z; d[3] = t[i].w; }
;         if (kb + 1 < kb1) {
; #pragma unroll
;             for (int i = 0; i < 8; ++i) t[i] = __builtin_nontemporal_load((const f32x4*)(W + (size_t)(k0 + 64 + (lane >> 3) + 8 * i) * N + n0 + 4 * (lane & 7))); }
;         f32x4 s0[NB], s1[NB];
;         if constexpr (WITH_SW) {
; #pragma unroll
;             for (int b = 0; b < NB; ++b) { s0[b] = *(const f32x4*)(shift + (size_t)b * 6 * D + k0 + 8 * c); s1[b] = *(const f32x4*)(shift + (size_t)b * 6 * D + k0 + 8 * c + 4); } }
;         asm volatile("s_waitcnt lgkmcnt(0)" ::: "memory");
; #pragma unroll
;         for (int j = 0; j < 4; ++j) { const int n = (lane >> 3) + 8 * j; const LAS float* sp = scr + (8 * c) * 33 + n;
;             u32x4 o; o.x = cvt_pk_bf16_c(sp[0 * 33], sp[1 * 33]); o.y = cvt_pk_bf16_c(sp[2 * 33], sp[3 * 33]); o.z = cvt_pk_bf16_c(sp[4 * 33], sp[5 * 33]); o.w = cvt_pk_bf16_c(sp[6 * 33], sp[7 * 33]);
;             if constexpr (TILED) __builtin_nontemporal_store(o, (u32x4*)(WT + (size_t)((r0 + n) >> 8) * ((size_t)256 * Kst) + (size_t)(k0 >> 6) * (256 * 64) + ((r0 + n) & 255) * 64 + 8 * c));
;             else *(u32x4*)(WT + (size_t)(r0 + n) * Kst + k0 + 8 * c) = o;
;             if constexpr (WITH_SW) { float wv[8]; unpack8(o, wv);
; #pragma unroll
;                 for (int b = 0; b < NB; ++b) a[j][b] += (s0[b].x * wv[0] + s0[b].y * wv[1]) + (s0[b].z * wv[2] + s0[b].w * wv[3]) + (s1[b].x * wv[4] + s1[b].y * wv[5]) + (s1[b].z * wv[6] + s1[b].w * wv[7]); } }
;         asm volatile("s_waitcnt lgkmcnt(0)" ::: "memory");
.LBB0_33:
	s_waitcnt lgkmcnt(0)
	ds_read2_b32 v[104:105], v74 offset0:33 offset1:41
	ds_read2_b32 v[106:107], v74 offset1:8
	ds_read2_b32 v[108:109], v74 offset0:66 offset1:74
	ds_read2_b32 v[110:111], v74 offset0:99 offset1:107
	ds_read2_b32 v[112:113], v74 offset0:132 offset1:140
	ds_read2_b32 v[114:115], v74 offset0:165 offset1:173
	ds_read2_b32 v[116:117], v74 offset0:198 offset1:206
	ds_read2_b32 v[118:119], v74 offset0:231 offset1:239
	s_waitcnt lgkmcnt(6)
	v_cvt_pk_bf16_f32 v100, v106, v104
	s_waitcnt lgkmcnt(4)
	v_cvt_pk_bf16_f32 v101, v108, v110
	s_waitcnt lgkmcnt(2)
	v_cvt_pk_bf16_f32 v102, v112, v114
	v_lshl_add_u64 v[120:121], v[64:65], 0, v[36:37]
	s_waitcnt lgkmcnt(0)
	v_cvt_pk_bf16_f32 v103, v116, v118
	global_store_dwordx4 v[120:121], v[100:103], off nt
	s_add_i32 s12, s12, 1
	v_lshl_add_u64 v[48:49], v[48:49], 0, s[4:5]
	v_cvt_pk_bf16_f32 v100, v107, v105
	v_cvt_pk_bf16_f32 v101, v109, v111
	v_cvt_pk_bf16_f32 v102, v113, v115
	v_cvt_pk_bf16_f32 v103, v117, v119
	ds_read2_b32 v[106:107], v74 offset0:16 offset1:24
	ds_read2_b32 v[108:109], v74 offset0:49 offset1:57
	ds_read2_b32 v[110:111], v74 offset0:82 offset1:90
	ds_read2_b32 v[112:113], v74 offset0:115 offset1:123
	ds_read2_b32 v[114:115], v74 offset0:148 offset1:156
	ds_read2_b32 v[116:117], v74 offset0:181 offset1:189
	ds_read2_b32 v[118:119], v74 offset0:214 offset1:222
	ds_read2_b32 v[120:121], v74 offset0:247 offset1:255
	v_lshl_add_u64 v[104:105], v[66:67], 0, v[36:37]
	global_store_dwordx4 v[104:105], v[100:103], off nt
	v_lshl_add_u64 v[104:105], v[68:69], 0, v[36:37]
	v_lshl_add_u64 v[50:51], v[50:51], 0, s[4:5]
	s_waitcnt lgkmcnt(6)
	v_cvt_pk_bf16_f32 v100, v106, v108
	s_waitcnt lgkmcnt(4)
	v_cvt_pk_bf16_f32 v101, v110, v112
	s_waitcnt lgkmcnt(2)
	v_cvt_pk_bf16_f32 v102, v114, v116
	s_waitcnt lgkmcnt(0)
	v_cvt_pk_bf16_f32 v103, v118, v120
	global_store_dwordx4 v[104:105], v[100:103], off nt
	v_lshl_add_u64 v[104:105], v[70:71], 0, v[36:37]
	v_lshl_add_u64 v[52:53], v[52:53], 0, s[4:5]
	v_cvt_pk_bf16_f32 v100, v107, v109
	v_cvt_pk_bf16_f32 v101, v111, v113
	v_cvt_pk_bf16_f32 v102, v115, v117
	v_cvt_pk_bf16_f32 v103, v119, v121
	global_store_dwordx4 v[104:105], v[100:103], off nt
	v_lshl_add_u64 v[54:55], v[54:55], 0, s[4:5]
	v_lshl_add_u64 v[56:57], v[56:57], 0, s[4:5]
	v_lshl_add_u64 v[58:59], v[58:59], 0, s[4:5]
	v_lshl_add_u64 v[60:61], v[60:61], 0, s[4:5]
	v_lshl_add_u64 v[62:63], v[62:63], 0, s[4:5]
	v_lshl_add_u64 v[64:65], v[64:65], 0, s[10:11]
	v_lshl_add_u64 v[66:67], v[66:67], 0, s[10:11]
	v_lshl_add_u64 v[68:69], v[68:69], 0, s[10:11]
	s_cmp_eq_u32 s12, 7
	v_lshl_add_u64 v[70:71], v[70:71], 0, s[10:11]
	s_cbranch_scc1 .LBB0_23

; __device__ __forceinline__ unsigned cvt_pk_bf16_c(float lo, float hi) { const f32x2_t v = {lo, hi}; return __builtin_bit_cast(unsigned, __builtin_convertvector(v, bf16x2_t)); }
; #define LAS __attribute__((address_space(3)))
; template <bool WITH_SW, bool TILED = false> __device__ __forceinline__ void wt_col_item(const float* W, int N, bf16_t* WT, int Kst, int kb0, int kb1, bool upmap, LAS float* scr, int nb, int lane, const float* shift, float* SWo) {
;     ...
;     for (int kb = kb0; kb < kb1; ++kb) { const int k0 = 64 * kb;
; #pragma unroll
;         for (int i = 0; i < 8; ++i) { LAS float* d = scr + ((lane >> 3) + 8 * i) * 33 + 4 * (lane & 7); d[0] = t[i].x; d[1] = t[i].y; d[2] = t[i].z; d[3] = t[i].w; }
;         if (kb + 1 < kb1) {
; #pragma unroll
;             for (int i = 0; i < 8; ++i) t[i] = __builtin_nontemporal_load((const f32x4*)(W + (size_t)(k0 + 64 + (lane >> 3) + 8 * i) * N + n0 + 4 * (lane & 7))); }
;         f32x4 s0[NB], s1[NB];
;         if constexpr (WITH_SW) {
; #pragma unroll
;             for (int b = 0; b < NB; ++b) { s0[b] = *(const f32x4*)(shift + (size_t)b * 6 * D + k0 + 8 * c); s1[b] = *(const f32x4*)(shift + (size_t)b * 6 * D + k0 + 8 * c + 4); } }
;         asm volatile("s_waitcnt lgkmcnt(0)" ::: "memory");
; #pragma unroll
;         for (int j = 0; j < 4; ++j) { const int n = (lane >> 3) + 8 * j; const LAS float* sp = scr + (8 * c) * 33 + n;
;             u32x4 o; o.x = cvt_pk_bf16_c(sp[0 * 33], sp[1 * 33]); o.y = cvt_pk_bf16_c(sp[2 * 33], sp[3 * 33]); o.z = cvt_pk_bf16_c(sp[4 * 33], sp[5 * 33]); o.w = cvt_pk_bf16_c(sp[6 * 33], sp[7 * 33]);
;             if constexpr (TILED) __builtin_nontemporal_store(o, (u32x4*)(WT + (size_t)((r0 + n) >> 8) * ((size_t)256 * Kst) + (size_t)(k0 >> 6) * (256 * 64) + ((r0 + n) & 255) * 64 + 8 * c));
;             else *(u32x4*)(WT + (size_t)(r0 + n) * Kst + k0 + 8 * c) = o;
;             if constexpr (WITH_SW) { float wv[8]; unpack8(o, wv);
; #pragma unroll
;                 for (int b = 0; b < NB; ++b) a[j][b] += (s0[b].x * wv[0] + s0[b].y * wv[1]) + (s0[b].z * wv[2] + s0[b].w * wv[3]) + (s1[b].x * wv[4] + s1[b].y * wv[5]) + (s1[b].z * wv[6] + s1[b].w * wv[7]); } }
.LBB0_166:
	v_add_u32_e32 v79, v144, v145
	v_add_u32_e32 v159, 0x1ce0, v79
	s_waitcnt vmcnt(7)
	ds_write2_b32 v79, v0, v1 offset1:1
	ds_write2_b32 v79, v2, v3 offset0:2 offset1:3
	s_waitcnt vmcnt(0)
	ds_write2_b32 v159, v28, v29 offset1:1
	v_lshl_add_u64 v[28:29], v[124:125], 0, v[58:59]
	s_mov_b32 s46, 0x2c0000
	v_add_co_u32_e32 v0, vcc, s46, v28
	v_add_u32_e32 v81, 0x420, v79
	s_nop 0
	v_addc_co_u32_e32 v1, vcc, 0, v29, vcc
	s_mov_b32 s46, 0x318000
	ds_write2_b32 v81, v4, v5 offset1:1
	v_add_co_u32_e32 v4, vcc, s46, v28
	v_add_u32_e32 v85, 0x840, v79
	s_nop 0
	v_addc_co_u32_e32 v5, vcc, 0, v29, vcc
	s_mov_b32 s46, 0x370000
	ds_write2_b32 v85, v8, v9 offset1:1
	v_add_co_u32_e32 v8, vcc, s46, v28
	v_add_u32_e32 v89, 0xc60, v79
	s_nop 0
	v_addc_co_u32_e32 v9, vcc, 0, v29, vcc
	s_mov_b32 s46, 0x3c8000
	ds_write2_b32 v89, v12, v13 offset1:1
	v_add_co_u32_e32 v12, vcc, s46, v28
	v_add_u32_e32 v153, 0x1080, v79
	s_nop 0
	v_addc_co_u32_e32 v13, vcc, 0, v29, vcc
	s_mov_b32 s46, 0x420000
	ds_write2_b32 v153, v16, v17 offset1:1
	v_add_co_u32_e32 v16, vcc, s46, v28
	v_add_u32_e32 v155, 0x14a0, v79
	s_nop 0
	v_addc_co_u32_e32 v17, vcc, 0, v29, vcc
	s_mov_b32 s46, 0x478000
	ds_write2_b32 v155, v20, v21 offset1:1
	v_add_co_u32_e32 v20, vcc, s46, v28
	v_add_u32_e32 v157, 0x18c0, v79
	s_nop 0
	v_addc_co_u32_e32 v21, vcc, 0, v29, vcc
	s_mov_b32 s46, 0x4d0000
	ds_write2_b32 v157, v24, v25 offset1:1
	v_add_co_u32_e32 v24, vcc, s46, v28
	s_mov_b32 s46, 0x528000
	s_nop 0
	v_addc_co_u32_e32 v25, vcc, 0, v29, vcc
	v_add_co_u32_e32 v28, vcc, s46, v28
	v_lshl_add_u64 v[126:127], v[122:123], 0, s[44:45]
	s_mov_b64 s[46:47], 0x106000
	v_addc_co_u32_e32 v29, vcc, 0, v29, vcc
	v_lshl_add_u64 v[32:33], v[126:127], 0, s[46:47]
	s_mov_b32 s46, 0x106000
	v_add_co_u32_e32 v34, vcc, s46, v126
	s_mov_b64 s[46:47], 0x112000
	s_nop 0
	v_addc_co_u32_e32 v35, vcc, 0, v127, vcc
	v_lshl_add_u64 v[40:41], v[126:127], 0, s[46:47]
	s_mov_b32 s46, 0x112000
	v_add_u32_e32 v83, 0x428, v79
	v_add_u32_e32 v87, 0x848, v79
	v_add_u32_e32 v91, 0xc68, v79
	v_add_u32_e32 v154, 0x1088, v79
	v_add_u32_e32 v156, 0x14a8, v79
	v_add_u32_e32 v158, 0x18c8, v79
	v_add_u32_e32 v160, 0x1ce8, v79
	v_add_co_u32_e32 v42, vcc, s46, v126
	ds_write2_b32 v83, v6, v7 offset1:1
	ds_write2_b32 v87, v10, v11 offset1:1
	ds_write2_b32 v91, v14, v15 offset1:1
	ds_write2_b32 v154, v18, v19 offset1:1
	ds_write2_b32 v156, v22, v23 offset1:1
	ds_write2_b32 v158, v26, v27 offset1:1
	ds_write2_b32 v160, v30, v31 offset1:1
	v_addc_co_u32_e32 v43, vcc, 0, v127, vcc
	global_load_dwordx4 v[0:3], v[0:1], off nt
	s_mov_b64 s[46:47], 0x11e000
	global_load_dwordx4 v[4:7], v[4:5], off nt
	v_lshl_add_u64 v[130:131], v[112:113], 0, v[58:59]
	global_load_dwordx4 v[8:11], v[8:9], off nt
	s_add_u32 s44, s44, 0x100
	global_load_dwordx4 v[12:15], v[12:13], off nt
	s_addc_u32 s45, s45, 0
	global_load_dwordx4 v[16:19], v[16:17], off nt
	v_lshl_add_u64 v[112:113], v[112:113], 0, s[14:15]
	global_load_dwordx4 v[20:23], v[20:21], off nt
	s_cmpk_eq_i32 s44, 0x1f00
	global_load_dwordx4 v[24:27], v[24:25], off nt
	s_nop 0
	global_load_dwordx4 v[28:31], v[28:29], off nt
	s_nop 0
	global_load_dwordx4 v[36:39], v[34:35], off
	s_nop 0
	global_load_dwordx4 v[32:35], v[32:33], off offset:16
	s_nop 0
	global_load_dwordx4 v[48:51], v[42:43], off
	global_load_dwordx4 v[132:135], v[40:41], off offset:16
	v_lshl_add_u64 v[40:41], v[126:127], 0, s[46:47]
	s_mov_b32 s46, 0x11e000
	v_add_co_u32_e32 v42, vcc, s46, v126
	s_mov_b64 s[46:47], 0x12a000
	s_nop 0
	v_addc_co_u32_e32 v43, vcc, 0, v127, vcc
	v_lshl_add_u64 v[128:129], v[126:127], 0, s[46:47]
	s_mov_b32 s46, 0x12a000
	v_add_co_u32_e32 v126, vcc, s46, v126
	global_load_dwordx4 v[44:47], v[42:43], off
	s_nop 0
	global_load_dwordx4 v[40:43], v[40:41], off offset:16
	v_addc_co_u32_e32 v127, vcc, 0, v127, vcc
	global_load_dwordx4 v[136:139], v[126:127], off
	global_load_dwordx4 v[162:165], v[128:129], off offset:16
	s_waitcnt lgkmcnt(0)
	ds_read2_b32 v[166:167], v146 offset0:33 offset1:41
	ds_read2_b32 v[168:169], v146 offset1:8
	ds_read2_b32 v[170:171], v146 offset0:66 offset1:74
	ds_read2_b32 v[172:173], v146 offset0:99 offset1:107
	ds_read2_b32 v[174:175], v146 offset0:132 offset1:140
	ds_read2_b32 v[176:177], v146 offset0:165 offset1:173
	ds_read2_b32 v[178:179], v146 offset0:198 offset1:206
	ds_read2_b32 v[180:181], v146 offset0:231 offset1:239
	s_mov_b64 s[46:47], 0x2c0000
	s_waitcnt lgkmcnt(6)
	v_cvt_pk_bf16_f32 v126, v168, v166
	s_waitcnt lgkmcnt(4)
	v_cvt_pk_bf16_f32 v127, v170, v172
	s_waitcnt lgkmcnt(2)
	v_cvt_pk_bf16_f32 v128, v174, v176
	s_waitcnt lgkmcnt(0)
	v_cvt_pk_bf16_f32 v129, v178, v180
	global_store_dwordx4 v[130:131], v[126:129], off nt
	v_and_b32_e32 v141, 0xffff0000, v126
	v_lshlrev_b32_e32 v140, 16, v126
	v_and_b32_e32 v183, 0xffff0000, v127
	v_lshlrev_b32_e32 v182, 16, v127
	v_and_b32_e32 v187, 0xffff0000, v129
	v_lshlrev_b32_e32 v186, 16, v129
	v_and_b32_e32 v185, 0xffff0000, v128
	v_lshlrev_b32_e32 v184, 16, v128
	v_lshl_add_u64 v[124:125], v[124:125], 0, s[46:47]
	s_waitcnt vmcnt(8)
	v_mov_b32_e32 v127, v37
	s_waitcnt vmcnt(6)
	v_mov_b32_e32 v37, v49
	v_mov_b32_e32 v129, v39
	v_mov_b32_e32 v39, v51
	v_mov_b32_e32 v126, v48
	v_pk_mul_f32 v[48:49], v[36:37], v[140:141]
	v_mov_b32_e32 v128, v50
	v_pk_mul_f32 v[50:51], v[38:39], v[182:183]
	v_pk_fma_f32 v[48:49], v[126:127], v[140:141], v[48:49] op_sel:[0,0,1] op_sel_hi:[1,1,0]
	v_pk_fma_f32 v[50:51], v[128:129], v[182:183], v[50:51] op_sel:[0,0,1] op_sel_hi:[1,1,0]
	v_mov_b32_e32 v131, v33
	s_waitcnt vmcnt(5)
; __device__ __forceinline__ unsigned cvt_pk_bf16_c(float lo, float hi) { const f32x2_t v = {lo, hi}; return __builtin_bit_cast(unsigned, __builtin_convertvector(v, bf16x2_t)); }
; #define LAS __attribute__((address_space(3)))
; template <bool WITH_SW, bool TILED = false> __device__ __forceinline__ void wt_col_item(const float* W, int N, bf16_t* WT, int Kst, int kb0, int kb1, bool upmap, LAS float* scr, int nb, int lane, const float* shift, float* SWo) {
;     ...
;         for (int j = 0; j < 4; ++j) { const int n = (lane >> 3) + 8 * j; const LAS float* sp = scr + (8 * c) * 33 + n;
;             u32x4 o; o.x = cvt_pk_bf16_c(sp[0 * 33], sp[1 * 33]); o.y = cvt_pk_bf16_c(sp[2 * 33], sp[3 * 33]); o.z = cvt_pk_bf16_c(sp[4 * 33], sp[5 * 33]); o.w = cvt_pk_bf16_c(sp[6 * 33], sp[7 * 33]);
;             if constexpr (TILED) __builtin_nontemporal_store(o, (u32x4*)(WT + (size_t)((r0 + n) >> 8) * ((size_t)256 * Kst) + (size_t)(k0 >> 6) * (256 * 64) + ((r0 + n) & 255) * 64 + 8 * c));
;             else *(u32x4*)(WT + (size_t)(r0 + n) * Kst + k0 + 8 * c) = o;
;             if constexpr (WITH_SW) { float wv[8]; unpack8(o, wv);
; #pragma unroll
;                 for (int b = 0; b < NB; ++b) a[j][b] += (s0[b].x * wv[0] + s0[b].y * wv[1]) + (s0[b].z * wv[2] + s0[b].w * wv[3]) + (s1[b].x * wv[4] + s1[b].y * wv[5]) + (s1[b].z * wv[6] + s1[b].w * wv[7]); } }
	v_mov_b32_e32 v33, v133
	v_pk_add_f32 v[48:49], v[48:49], v[50:51]
	v_mov_b32_e32 v130, v132
	v_pk_mul_f32 v[50:51], v[32:33], v[184:185]
	v_mov_b32_e32 v133, v35
	v_pk_fma_f32 v[50:51], v[130:131], v[184:185], v[50:51] op_sel:[0,0,1] op_sel_hi:[1,1,0]
	v_mov_b32_e32 v35, v135
	v_pk_add_f32 v[48:49], v[48:49], v[50:51]
	v_mov_b32_e32 v132, v134
	v_pk_mul_f32 v[50:51], v[34:35], v[186:187]
	s_waitcnt vmcnt(2)
	v_mov_b32_e32 v134, v136
	v_pk_fma_f32 v[50:51], v[132:133], v[186:187], v[50:51] op_sel:[0,0,1] op_sel_hi:[1,1,0]
	v_mov_b32_e32 v135, v45
	v_pk_add_f32 v[48:49], v[48:49], v[50:51]
	v_mov_b32_e32 v45, v137
	v_mov_b32_e32 v136, v138
	v_mov_b32_e32 v137, v47
	v_pk_add_f32 v[106:107], v[106:107], v[48:49]
	v_pk_mul_f32 v[48:49], v[134:135], v[140:141]
	v_pk_mul_f32 v[50:51], v[136:137], v[182:183]
	v_mov_b32_e32 v47, v139
	v_pk_fma_f32 v[48:49], v[44:45], v[140:141], v[48:49] op_sel:[0,0,1] op_sel_hi:[1,1,0]
	v_pk_fma_f32 v[50:51], v[46:47], v[182:183], v[50:51] op_sel:[0,0,1] op_sel_hi:[1,1,0]
	s_waitcnt vmcnt(1)
	v_mov_b32_e32 v138, v162
	v_mov_b32_e32 v139, v41
	v_pk_add_f32 v[48:49], v[48:49], v[50:51]
	v_pk_mul_f32 v[50:51], v[138:139], v[184:185]
	v_mov_b32_e32 v41, v163
	v_pk_fma_f32 v[50:51], v[40:41], v[184:185], v[50:51] op_sel:[0,0,1] op_sel_hi:[1,1,0]
	v_mov_b32_e32 v140, v164
	v_mov_b32_e32 v141, v43
	v_pk_add_f32 v[48:49], v[48:49], v[50:51]
	v_pk_mul_f32 v[50:51], v[140:141], v[186:187]
	v_mov_b32_e32 v43, v165
	v_pk_fma_f32 v[50:51], v[42:43], v[186:187], v[50:51] op_sel:[0,0,1] op_sel_hi:[1,1,0]
	v_lshl_add_u64 v[162:163], v[116:117], 0, v[58:59]
	v_pk_add_f32 v[48:49], v[48:49], v[50:51]
	v_cvt_pk_bf16_f32 v50, v175, v177
	v_pk_add_f32 v[104:105], v[104:105], v[48:49]
	v_cvt_pk_bf16_f32 v48, v169, v167
	v_cvt_pk_bf16_f32 v49, v171, v173
	v_cvt_pk_bf16_f32 v51, v179, v181
	global_store_dwordx4 v[162:163], v[48:51], off nt
	v_and_b32_e32 v163, 0xffff0000, v48
	v_lshlrev_b32_e32 v162, 16, v48
	v_and_b32_e32 v165, 0xffff0000, v49
	v_lshlrev_b32_e32 v164, 16, v49
	v_and_b32_e32 v49, 0xffff0000, v50
	v_lshlrev_b32_e32 v48, 16, v50
	v_and_b32_e32 v167, 0xffff0000, v51
	v_lshlrev_b32_e32 v166, 16, v51
	v_pk_mul_f32 v[50:51], v[36:37], v[162:163]
	v_pk_mul_f32 v[168:169], v[38:39], v[164:165]
	v_pk_fma_f32 v[50:51], v[126:127], v[162:163], v[50:51] op_sel:[0,0,1] op_sel_hi:[1,1,0]
	v_pk_fma_f32 v[168:169], v[128:129], v[164:165], v[168:169] op_sel:[0,0,1] op_sel_hi:[1,1,0]
	v_lshl_add_u64 v[178:179], v[118:119], 0, v[58:59]
	v_pk_add_f32 v[50:51], v[50:51], v[168:169]
	v_pk_mul_f32 v[168:169], v[32:33], v[48:49]
	v_lshl_add_u64 v[116:117], v[116:117], 0, s[14:15]
	v_pk_fma_f32 v[168:169], v[130:131], v[48:49], v[168:169] op_sel:[0,0,1] op_sel_hi:[1,1,0]
	v_lshl_add_u64 v[118:119], v[118:119], 0, s[14:15]
	v_pk_add_f32 v[50:51], v[50:51], v[168:169]
	v_pk_mul_f32 v[168:169], v[34:35], v[166:167]
	s_nop 0
	v_pk_fma_f32 v[168:169], v[132:133], v[166:167], v[168:169] op_sel:[0,0,1] op_sel_hi:[1,1,0]
	s_nop 0
	v_pk_add_f32 v[50:51], v[50:51], v[168:169]
	s_nop 0
	v_pk_add_f32 v[102:103], v[102:103], v[50:51]
	v_pk_mul_f32 v[50:51], v[134:135], v[162:163]
	s_nop 0
	v_pk_fma_f32 v[50:51], v[44:45], v[162:163], v[50:51] op_sel:[0,0,1] op_sel_hi:[1,1,0]
	v_pk_mul_f32 v[162:163], v[136:137], v[164:165]
	s_nop 0
	v_pk_fma_f32 v[162:163], v[46:47], v[164:165], v[162:163] op_sel:[0,0,1] op_sel_hi:[1,1,0]
	s_nop 0
	v_pk_add_f32 v[50:51], v[50:51], v[162:163]
	v_pk_mul_f32 v[162:163], v[138:139], v[48:49]
	s_nop 0
	v_pk_fma_f32 v[48:49], v[40:41], v[48:49], v[162:163] op_sel:[0,0,1] op_sel_hi:[1,1,0]
	ds_read2_b32 v[162:163], v146 offset0:16 offset1:24
	ds_read2_b32 v[164:165], v146 offset0:49 offset1:57
	v_pk_add_f32 v[48:49], v[50:51], v[48:49]
	v_pk_mul_f32 v[50:51], v[140:141], v[166:167]
	s_nop 0
	v_pk_fma_f32 v[50:51], v[42:43], v[166:167], v[50:51] op_sel:[0,0,1] op_sel_hi:[1,1,0]
	ds_read2_b32 v[166:167], v146 offset0:82 offset1:90
	ds_read2_b32 v[168:169], v146 offset0:115 offset1:123
	ds_read2_b32 v[170:171], v146 offset0:148 offset1:156
	ds_read2_b32 v[172:173], v146 offset0:181 offset1:189
	ds_read2_b32 v[174:175], v146 offset0:214 offset1:222
	ds_read2_b32 v[176:177], v146 offset0:247 offset1:255
	v_pk_add_f32 v[48:49], v[48:49], v[50:51]
	s_waitcnt lgkmcnt(2)
	v_cvt_pk_bf16_f32 v50, v170, v172
	v_pk_add_f32 v[100:101], v[100:101], v[48:49]
	v_cvt_pk_bf16_f32 v48, v162, v164
	v_cvt_pk_bf16_f32 v49, v166, v168
	s_waitcnt lgkmcnt(0)
; __device__ __forceinline__ unsigned cvt_pk_bf16_c(float lo, float hi) { const f32x2_t v = {lo, hi}; return __builtin_bit_cast(unsigned, __builtin_convertvector(v, bf16x2_t)); }
; #define LAS __attribute__((address_space(3)))
; template <bool WITH_SW, bool TILED = false> __device__ __forceinline__ void wt_col_item(const float* W, int N, bf16_t* WT, int Kst, int kb0, int kb1, bool upmap, LAS float* scr, int nb, int lane, const float* shift, float* SWo) {
;     ...
;         for (int j = 0; j < 4; ++j) { const int n = (lane >> 3) + 8 * j; const LAS float* sp = scr + (8 * c) * 33 + n;
;             u32x4 o; o.x = cvt_pk_bf16_c(sp[0 * 33], sp[1 * 33]); o.y = cvt_pk_bf16_c(sp[2 * 33], sp[3 * 33]); o.z = cvt_pk_bf16_c(sp[4 * 33], sp[5 * 33]); o.w = cvt_pk_bf16_c(sp[6 * 33], sp[7 * 33]);
;             if constexpr (TILED) __builtin_nontemporal_store(o, (u32x4*)(WT + (size_t)((r0 + n) >> 8) * ((size_t)256 * Kst) + (size_t)(k0 >> 6) * (256 * 64) + ((r0 + n) & 255) * 64 + 8 * c));
;             else *(u32x4*)(WT + (size_t)(r0 + n) * Kst + k0 + 8 * c) = o;
;             if constexpr (WITH_SW) { float wv[8]; unpack8(o, wv);
; #pragma unroll
;                 for (int b = 0; b < NB; ++b) a[j][b] += (s0[b].x * wv[0] + s0[b].y * wv[1]) + (s0[b].z * wv[2] + s0[b].w * wv[3]) + (s1[b].x * wv[4] + s1[b].y * wv[5]) + (s1[b].z * wv[6] + s1[b].w * wv[7]); } }
;         asm volatile("s_waitcnt lgkmcnt(0)" ::: "memory");
;     }
	v_cvt_pk_bf16_f32 v51, v174, v176
	global_store_dwordx4 v[178:179], v[48:51], off nt
	v_and_b32_e32 v179, 0xffff0000, v48
	v_lshlrev_b32_e32 v178, 16, v48
	v_and_b32_e32 v181, 0xffff0000, v49
	v_lshlrev_b32_e32 v180, 16, v49
	v_and_b32_e32 v49, 0xffff0000, v50
	v_lshlrev_b32_e32 v48, 16, v50
	v_and_b32_e32 v183, 0xffff0000, v51
	v_lshlrev_b32_e32 v182, 16, v51
	v_pk_mul_f32 v[50:51], v[36:37], v[178:179]
	v_pk_mul_f32 v[184:185], v[38:39], v[180:181]
	v_pk_fma_f32 v[50:51], v[126:127], v[178:179], v[50:51] op_sel:[0,0,1] op_sel_hi:[1,1,0]
	v_pk_fma_f32 v[184:185], v[128:129], v[180:181], v[184:185] op_sel:[0,0,1] op_sel_hi:[1,1,0]
	s_nop 0
	v_pk_add_f32 v[50:51], v[50:51], v[184:185]
	v_pk_mul_f32 v[184:185], v[32:33], v[48:49]
	s_nop 0
	v_pk_fma_f32 v[184:185], v[130:131], v[48:49], v[184:185] op_sel:[0,0,1] op_sel_hi:[1,1,0]
	s_nop 0
	v_pk_add_f32 v[50:51], v[50:51], v[184:185]
	v_pk_mul_f32 v[184:185], v[34:35], v[182:183]
	s_nop 0
	v_pk_fma_f32 v[184:185], v[132:133], v[182:183], v[184:185] op_sel:[0,0,1] op_sel_hi:[1,1,0]
	s_nop 0
	v_pk_add_f32 v[50:51], v[50:51], v[184:185]
	s_nop 0
	v_pk_add_f32 v[98:99], v[98:99], v[50:51]
	v_pk_mul_f32 v[50:51], v[134:135], v[178:179]
	s_nop 0
	v_pk_fma_f32 v[50:51], v[44:45], v[178:179], v[50:51] op_sel:[0,0,1] op_sel_hi:[1,1,0]
	v_pk_mul_f32 v[178:179], v[136:137], v[180:181]
	s_nop 0
	v_pk_fma_f32 v[178:179], v[46:47], v[180:181], v[178:179] op_sel:[0,0,1] op_sel_hi:[1,1,0]
	s_nop 0
	v_pk_add_f32 v[50:51], v[50:51], v[178:179]
	v_pk_mul_f32 v[178:179], v[138:139], v[48:49]
	s_nop 0
	v_pk_fma_f32 v[48:49], v[40:41], v[48:49], v[178:179] op_sel:[0,0,1] op_sel_hi:[1,1,0]
	s_nop 0
	v_pk_add_f32 v[48:49], v[50:51], v[48:49]
	v_pk_mul_f32 v[50:51], v[140:141], v[182:183]
	s_nop 0
	v_pk_fma_f32 v[50:51], v[42:43], v[182:183], v[50:51] op_sel:[0,0,1] op_sel_hi:[1,1,0]
	s_nop 0
	v_pk_add_f32 v[48:49], v[48:49], v[50:51]
	v_cvt_pk_bf16_f32 v50, v171, v173
	v_pk_add_f32 v[96:97], v[96:97], v[48:49]
	v_cvt_pk_bf16_f32 v48, v163, v165
	v_cvt_pk_bf16_f32 v49, v167, v169
	v_cvt_pk_bf16_f32 v51, v175, v177
	v_lshl_add_u64 v[162:163], v[120:121], 0, v[58:59]
	global_store_dwordx4 v[162:163], v[48:51], off nt
	v_and_b32_e32 v163, 0xffff0000, v48
	v_lshlrev_b32_e32 v162, 16, v48
	v_and_b32_e32 v165, 0xffff0000, v49
	v_lshlrev_b32_e32 v164, 16, v49
	v_and_b32_e32 v49, 0xffff0000, v50
	v_lshlrev_b32_e32 v48, 16, v50
	v_pk_mul_f32 v[36:37], v[36:37], v[162:163]
	v_pk_mul_f32 v[38:39], v[38:39], v[164:165]
	v_and_b32_e32 v167, 0xffff0000, v51
	v_lshlrev_b32_e32 v166, 16, v51
	v_pk_fma_f32 v[36:37], v[126:127], v[162:163], v[36:37] op_sel:[0,0,1] op_sel_hi:[1,1,0]
	v_pk_fma_f32 v[38:39], v[128:129], v[164:165], v[38:39] op_sel:[0,0,1] op_sel_hi:[1,1,0]
	v_pk_mul_f32 v[32:33], v[32:33], v[48:49]
	v_pk_add_f32 v[36:37], v[36:37], v[38:39]
	v_pk_fma_f32 v[32:33], v[130:131], v[48:49], v[32:33] op_sel:[0,0,1] op_sel_hi:[1,1,0]
	v_pk_mul_f32 v[34:35], v[34:35], v[166:167]
	v_pk_add_f32 v[32:33], v[36:37], v[32:33]
	v_pk_fma_f32 v[34:35], v[132:133], v[166:167], v[34:35] op_sel:[0,0,1] op_sel_hi:[1,1,0]
	v_lshl_add_u64 v[120:121], v[120:121], 0, s[14:15]
	v_pk_add_f32 v[32:33], v[32:33], v[34:35]
	v_pk_mul_f32 v[34:35], v[136:137], v[164:165]
	v_pk_add_f32 v[94:95], v[94:95], v[32:33]
	v_pk_mul_f32 v[32:33], v[134:135], v[162:163]
	v_pk_fma_f32 v[34:35], v[46:47], v[164:165], v[34:35] op_sel:[0,0,1] op_sel_hi:[1,1,0]
	v_pk_fma_f32 v[32:33], v[44:45], v[162:163], v[32:33] op_sel:[0,0,1] op_sel_hi:[1,1,0]
	s_nop 0
	v_pk_add_f32 v[32:33], v[32:33], v[34:35]
	v_pk_mul_f32 v[34:35], v[138:139], v[48:49]
	s_nop 0
	v_pk_fma_f32 v[34:35], v[40:41], v[48:49], v[34:35] op_sel:[0,0,1] op_sel_hi:[1,1,0]
	s_nop 0
	v_pk_add_f32 v[32:33], v[32:33], v[34:35]
	v_pk_mul_f32 v[34:35], v[140:141], v[166:167]
	s_nop 0
	v_pk_fma_f32 v[34:35], v[42:43], v[166:167], v[34:35] op_sel:[0,0,1] op_sel_hi:[1,1,0]
	s_nop 0
	v_pk_add_f32 v[32:33], v[32:33], v[34:35]
	s_nop 0
	v_pk_add_f32 v[92:93], v[92:93], v[32:33]
	s_cbranch_scc0 .LBB0_166
; #define LAS __attribute__((address_space(3)))
; template <bool WITH_SW, bool TILED = false> __device__ __forceinline__ void wt_col_item(const float* W, int N, bf16_t* WT, int Kst, int kb0, int kb1, bool upmap, LAS float* scr, int nb, int lane, const float* shift, float* SWo) {
;     ...
;     for (int kb = kb0; kb < kb1; ++kb) { const int k0 = 64 * kb;
; #pragma unroll
;         for (int i = 0; i < 8; ++i) { LAS float* d = scr + ((lane >> 3) + 8 * i) * 33 + 4 * (lane & 7); d[0] = t[i].x; d[1] = t[i].y; d[2] = t[i].z; d[3] = t[i].w; }
;         if (kb + 1 < kb1) {
; #pragma unroll
;             for (int i = 0; i < 8; ++i) t[i] = __builtin_nontemporal_load((const f32x4*)(W + (size_t)(k0 + 64 + (lane >> 3) + 8 * i) * N + n0 + 4 * (lane & 7))); }
;         f32x4 s0[NB], s1[NB];
;         if constexpr (WITH_SW) {
; #pragma unroll
;             for (int b = 0; b < NB; ++b) { s0[b] = *(const f32x4*)(shift + (size_t)b * 6 * D + k0 + 8 * c); s1[b] = *(const f32x4*)(shift + (size_t)b * 6 * D + k0 + 8 * c + 4); } }
;         asm volatile("s_waitcnt lgkmcnt(0)" ::: "memory");
; #pragma unroll
;         for (int j = 0; j < 4; ++j) { const int n = (lane >> 3) + 8 * j; const LAS float* sp = scr + (8 * c) * 33 + n;
;             u32x4 o; o.x = cvt_pk_bf16_c(sp[0 * 33], sp[1 * 33]); o.y = cvt_pk_bf16_c(sp[2 * 33], sp[3 * 33]); o.z = cvt_pk_bf16_c(sp[4 * 33], sp[5 * 33]); o.w = cvt_pk_bf16_c(sp[6 * 33], sp[7 * 33]);
;             if constexpr (TILED) __builtin_nontemporal_store(o, (u32x4*)(WT + (size_t)((r0 + n) >> 8) * ((size_t)256 * Kst) + (size_t)(k0 >> 6) * (256 * 64) + ((r0 + n) & 255) * 64 + 8 * c));
;             else *(u32x4*)(WT + (size_t)(r0 + n) * Kst + k0 + 8 * c) = o;
;             if constexpr (WITH_SW) { float wv[8]; unpack8(o, wv);
; #pragma unroll
;                 for (int b = 0; b < NB; ++b) a[j][b] += (s0[b].x * wv[0] + s0[b].y * wv[1]) + (s0[b].z * wv[2] + s0[b].w * wv[3]) + (s1[b].x * wv[4] + s1[b].y * wv[5]) + (s1[b].z * wv[6] + s1[b].w * wv[7]); } }
;         asm volatile("s_waitcnt lgkmcnt(0)" ::: "memory");
;     }
;     if constexpr (WITH_SW) {
; #pragma unroll
;         for (int j = 0; j < 4; ++j)
; #pragma unroll
;             for (int b = 0; b < NB; ++b) { float v = a[j][b]; v += bperm(v, lane ^ 1); v += bperm(v, lane ^ 2); v += bperm(v, lane ^ 4);
;                 if (c == 0) SWo[(size_t)b * N + r0 + (lane >> 3) + 8 * j] = v; } }
	s_add_u32 s44, s4, s36
	s_addc_u32 s45, s5, s37
	v_lshlrev_b32_e32 v32, 2, v60
	v_mov_b32_e32 v33, v57
	s_add_u32 s43, s39, s43
	v_lshl_add_u64 v[36:37], s[44:45], 0, v[32:33]
	s_addc_u32 s45, s40, s10
	s_mul_i32 s10, s67, 0x2c000
	s_mul_hi_i32 s44, s67, 0x2c000
	s_add_u32 s10, s41, s10
	s_addc_u32 s46, s48, s44
	s_movk_i32 s44, 0x7000
	ds_write2_b32 v79, v0, v1 offset1:1
	ds_write2_b32 v79, v2, v3 offset0:2 offset1:3
	ds_write2_b32 v81, v4, v5 offset1:1
	ds_write2_b32 v83, v6, v7 offset1:1
	ds_write2_b32 v85, v8, v9 offset1:1
	ds_write2_b32 v87, v10, v11 offset1:1
	ds_write2_b32 v89, v12, v13 offset1:1
	ds_write2_b32 v91, v14, v15 offset1:1
	ds_write2_b32 v153, v16, v17 offset1:1
	ds_write2_b32 v154, v18, v19 offset1:1
	ds_write2_b32 v155, v20, v21 offset1:1
	ds_write2_b32 v156, v22, v23 offset1:1
	ds_write2_b32 v157, v24, v25 offset1:1
	ds_write2_b32 v158, v26, v27 offset1:1
	ds_write2_b32 v159, v28, v29 offset1:1
	ds_write2_b32 v160, v30, v31 offset1:1
	v_add_co_u32_e32 v0, vcc, s44, v36
	s_mov_b64 s[68:69], 0x7f00
	s_nop 0
	v_addc_co_u32_e32 v1, vcc, 0, v37, vcc
	v_lshl_add_u64 v[4:5], v[36:37], 0, s[68:69]
	global_load_dwordx4 v[0:3], v[0:1], off offset:3840
	s_nop 0
	global_load_dwordx4 v[8:11], v[4:5], off offset:16
	s_mov_b32 s44, 0x13000
	v_add_co_u32_e32 v6, vcc, s44, v36
	s_mov_b64 s[68:69], 0x13f00
	s_nop 0
	v_addc_co_u32_e32 v7, vcc, 0, v37, vcc
	s_mov_b32 s44, 0x1f000
	v_lshl_add_u64 v[4:5], v[36:37], 0, s[68:69]
	global_load_dwordx4 v[28:31], v[6:7], off offset:3840
	global_load_dwordx4 v[24:27], v[4:5], off offset:16
	v_add_co_u32_e32 v6, vcc, s44, v36
	s_mov_b64 s[68:69], 0x1ff00
	s_nop 0
	v_addc_co_u32_e32 v7, vcc, 0, v37, vcc
	s_mov_b32 s44, 0x2b000
	v_lshl_add_u64 v[4:5], v[36:37], 0, s[68:69]
	global_load_dwordx4 v[20:23], v[6:7], off offset:3840
	global_load_dwordx4 v[16:19], v[4:5], off offset:16
	s_mov_b64 s[68:69], 0x2bf00
	v_add_co_u32_e32 v6, vcc, s44, v36
	v_lshl_add_u64 v[4:5], v[36:37], 0, s[68:69]
	s_nop 0
	v_addc_co_u32_e32 v7, vcc, 0, v37, vcc
	global_load_dwordx4 v[12:15], v[6:7], off offset:3840
	s_nop 0
	global_load_dwordx4 v[4:7], v[4:5], off offset:16
	s_waitcnt lgkmcnt(0)
	ds_read2_b32 v[40:41], v146 offset0:33 offset1:41
	ds_read2_b32 v[42:43], v146 offset1:8
	v_mov_b32_e32 v111, v57
	v_lshlrev_b64 v[32:33], 20, v[110:111]
	v_mov_b32_e32 v115, v57
	ds_read2_b32 v[110:111], v146 offset0:66 offset1:74
	ds_read2_b32 v[112:113], v146 offset0:99 offset1:107
	v_lshlrev_b64 v[44:45], 20, v[114:115]
	ds_read2_b32 v[114:115], v146 offset0:132 offset1:140
	ds_read2_b32 v[116:117], v146 offset0:165 offset1:173
	ds_read2_b32 v[118:119], v146 offset0:198 offset1:206
	ds_read2_b32 v[120:121], v146 offset0:231 offset1:239
	s_add_u32 s44, s43, 0xf8000
	s_addc_u32 s45, s45, 0
	s_waitcnt lgkmcnt(6)
	v_cvt_pk_bf16_f32 v36, v42, v40
	v_lshlrev_b32_e32 v40, 7, v77
	v_lshlrev_b64 v[34:35], 20, v[56:57]
	v_lshl_add_u64 v[46:47], s[44:45], 0, v[108:109]
	v_and_b32_e32 v56, 0x7f80, v40
	s_waitcnt lgkmcnt(4)
	v_cvt_pk_bf16_f32 v37, v110, v112
	v_lshl_add_u64 v[46:47], v[46:47], 0, v[56:57]
	v_lshlrev_b32_e32 v56, 1, v60
	s_waitcnt lgkmcnt(2)
	v_cvt_pk_bf16_f32 v38, v114, v116
	s_waitcnt lgkmcnt(0)
	v_cvt_pk_bf16_f32 v39, v118, v120
	v_lshl_add_u64 v[46:47], v[46:47], 0, v[56:57]
	v_and_b32_e32 v79, 0xffff0000, v36
	v_and_b32_e32 v77, 0xffff0000, v37
	global_store_dwordx4 v[46:47], v[36:39], off nt
	v_lshlrev_b32_e32 v50, 16, v36
	v_lshlrev_b32_e32 v49, 16, v37
	v_and_b32_e32 v51, 0xffff0000, v38
	v_lshlrev_b32_e32 v47, 16, v38
	v_and_b32_e32 v48, 0xffff0000, v39
	v_lshlrev_b32_e32 v46, 16, v39
	v_lshl_add_u64 v[34:35], s[44:45], 0, v[34:35]
	v_cvt_pk_bf16_f32 v40, v43, v41
	v_cvt_pk_bf16_f32 v41, v111, v113
	v_cvt_pk_bf16_f32 v42, v115, v117
	v_cvt_pk_bf16_f32 v43, v119, v121
	v_lshl_add_u64 v[32:33], s[44:45], 0, v[32:33]
	v_mov_b32_e32 v123, v57
	v_lshlrev_b32_e32 v71, 7, v71
	s_mov_b32 s43, s11
	v_lshl_add_u64 v[44:45], s[44:45], 0, v[44:45]
	s_lshl_b64 s[42:43], s[42:43], 2
	s_add_u32 s42, s10, s42
	s_addc_u32 s43, s46, s43
	s_waitcnt vmcnt(8)
	v_mul_f32_e32 v36, v1, v79
	v_mul_f32_e32 v37, v3, v77
	v_fmac_f32_e32 v36, v0, v50
	v_fmac_f32_e32 v37, v2, v49
	v_add_f32_e32 v36, v36, v37
	s_waitcnt vmcnt(7)
	v_mul_f32_e32 v37, v9, v51
	v_fmac_f32_e32 v37, v8, v47
	v_add_f32_e32 v36, v36, v37
	v_mul_f32_e32 v37, v11, v48
	v_fmac_f32_e32 v37, v10, v46
	v_add_f32_e32 v36, v36, v37
	v_add_f32_e32 v81, v107, v36
	v_lshlrev_b32_e32 v36, 7, v75
	v_and_b32_e32 v36, 0x7f80, v36
	v_mov_b32_e32 v37, v57
	v_lshl_add_u64 v[34:35], v[34:35], 0, v[36:37]
	v_lshl_add_u64 v[34:35], v[34:35], 0, v[56:57]
	global_store_dwordx4 v[34:35], v[40:43], off nt
	ds_read2_b32 v[34:35], v146 offset0:16 offset1:24
	ds_read2_b32 v[108:109], v146 offset0:49 offset1:57
	ds_read2_b32 v[110:111], v146 offset0:82 offset1:90
	ds_read2_b32 v[112:113], v146 offset0:115 offset1:123
	ds_read2_b32 v[114:115], v146 offset0:148 offset1:156
	ds_read2_b32 v[116:117], v146 offset0:181 offset1:189
	ds_read2_b32 v[118:119], v146 offset0:214 offset1:222
	ds_read2_b32 v[120:121], v146 offset0:247 offset1:255
	s_waitcnt lgkmcnt(6)
	v_cvt_pk_bf16_f32 v36, v34, v108
	v_lshlrev_b32_e32 v34, 7, v73
	v_and_b32_e32 v122, 0x7f80, v34
	v_lshl_add_u64 v[32:33], v[32:33], 0, v[122:123]
	s_waitcnt lgkmcnt(4)
	v_cvt_pk_bf16_f32 v37, v110, v112
	s_waitcnt lgkmcnt(2)
	v_cvt_pk_bf16_f32 v38, v114, v116
	s_waitcnt lgkmcnt(0)
	v_cvt_pk_bf16_f32 v39, v118, v120
	v_lshl_add_u64 v[32:33], v[32:33], 0, v[56:57]
	global_store_dwordx4 v[32:33], v[36:39], off nt
	v_cvt_pk_bf16_f32 v32, v35, v109
	v_and_b32_e32 v108, 0x7f80, v71
	v_mov_b32_e32 v109, v57
	v_lshl_add_u64 v[44:45], v[44:45], 0, v[108:109]
	v_cvt_pk_bf16_f32 v33, v111, v113
	v_cvt_pk_bf16_f32 v34, v115, v117
	v_cvt_pk_bf16_f32 v35, v119, v121
	v_lshl_add_u64 v[44:45], v[44:45], 0, v[56:57]
	v_lshlrev_b32_e32 v56, 2, v54
	global_store_dwordx4 v[44:45], v[32:35], off nt
	v_lshl_add_u64 v[44:45], s[42:43], 0, v[56:57]
	ds_bpermute_b32 v56, v147, v81
	s_waitcnt lgkmcnt(0)
	v_add_f32_e32 v56, v81, v56
	ds_bpermute_b32 v71, v148, v56
	s_waitcnt lgkmcnt(0)
	v_add_f32_e32 v56, v56, v71
	ds_bpermute_b32 v71, v149, v56
	s_and_saveexec_b64 s[42:43], s[0:1]
	s_cbranch_execz .LBB0_169
	s_waitcnt lgkmcnt(0)
	v_add_f32_e32 v56, v56, v71
	global_store_dword v[44:45], v56, off

; __device__ __forceinline__ unsigned cvt_pk_bf16_c(float lo, float hi) { const f32x2_t v = {lo, hi}; return __builtin_bit_cast(unsigned, __builtin_convertvector(v, bf16x2_t)); }
; #define LAS __attribute__((address_space(3)))
; template <bool WITH_SW, bool TILED = false> __device__ __forceinline__ void wt_col_item(const float* W, int N, bf16_t* WT, int Kst, int kb0, int kb1, bool upmap, LAS float* scr, int nb, int lane, const float* shift, float* SWo) {
;     ...
;     for (int kb = kb0; kb < kb1; ++kb) { const int k0 = 64 * kb;
; #pragma unroll
;         for (int i = 0; i < 8; ++i) { LAS float* d = scr + ((lane >> 3) + 8 * i) * 33 + 4 * (lane & 7); d[0] = t[i].x; d[1] = t[i].y; d[2] = t[i].z; d[3] = t[i].w; }
;         if (kb + 1 < kb1) {
; #pragma unroll
;             for (int i = 0; i < 8; ++i) t[i] = __builtin_nontemporal_load((const f32x4*)(W + (size_t)(k0 + 64 + (lane >> 3) + 8 * i) * N + n0 + 4 * (lane & 7))); }
;         f32x4 s0[NB], s1[NB];
;         if constexpr (WITH_SW) {
; #pragma unroll
;             for (int b = 0; b < NB; ++b) { s0[b] = *(const f32x4*)(shift + (size_t)b * 6 * D + k0 + 8 * c); s1[b] = *(const f32x4*)(shift + (size_t)b * 6 * D + k0 + 8 * c + 4); } }
;         asm volatile("s_waitcnt lgkmcnt(0)" ::: "memory");
; #pragma unroll
;         for (int j = 0; j < 4; ++j) { const int n = (lane >> 3) + 8 * j; const LAS float* sp = scr + (8 * c) * 33 + n;
;             u32x4 o; o.x = cvt_pk_bf16_c(sp[0 * 33], sp[1 * 33]); o.y = cvt_pk_bf16_c(sp[2 * 33], sp[3 * 33]); o.z = cvt_pk_bf16_c(sp[4 * 33], sp[5 * 33]); o.w = cvt_pk_bf16_c(sp[6 * 33], sp[7 * 33]);
;             if constexpr (TILED) __builtin_nontemporal_store(o, (u32x4*)(WT + (size_t)((r0 + n) >> 8) * ((size_t)256 * Kst) + (size_t)(k0 >> 6) * (256 * 64) + ((r0 + n) & 255) * 64 + 8 * c));
;             else *(u32x4*)(WT + (size_t)(r0 + n) * Kst + k0 + 8 * c) = o;
;             if constexpr (WITH_SW) { float wv[8]; unpack8(o, wv);
; #pragma unroll
;                 for (int b = 0; b < NB; ++b) a[j][b] += (s0[b].x * wv[0] + s0[b].y * wv[1]) + (s0[b].z * wv[2] + s0[b].w * wv[3]) + (s1[b].x * wv[4] + s1[b].y * wv[5]) + (s1[b].z * wv[6] + s1[b].w * wv[7]); } }
.LBB0_201:
	v_add_u32_e32 v56, v144, v145
	v_add_u32_e32 v137, 0x1ce0, v56
	s_waitcnt vmcnt(7)
	ds_write2_b32 v56, v0, v1 offset1:1
	ds_write2_b32 v56, v2, v3 offset0:2 offset1:3
	s_waitcnt vmcnt(0)
	ds_write2_b32 v137, v28, v29 offset1:1
	v_lshl_add_u64 v[28:29], v[118:119], 0, v[58:59]
	s_mov_b32 s68, 0x140000
	v_add_co_u32_e32 v0, vcc, s68, v28
	v_add_u32_e32 v71, 0x420, v56
	s_nop 0
	v_addc_co_u32_e32 v1, vcc, 0, v29, vcc
	s_mov_b32 s68, 0x168000
	ds_write2_b32 v71, v4, v5 offset1:1
	v_add_co_u32_e32 v4, vcc, s68, v28
	v_add_u32_e32 v75, 0x840, v56
	s_nop 0
	v_addc_co_u32_e32 v5, vcc, 0, v29, vcc
	s_mov_b32 s68, 0x190000
	ds_write2_b32 v75, v8, v9 offset1:1
	v_add_co_u32_e32 v8, vcc, s68, v28
	v_add_u32_e32 v79, 0xc60, v56
	s_nop 0
	v_addc_co_u32_e32 v9, vcc, 0, v29, vcc
	s_mov_b32 s68, 0x1b8000
	ds_write2_b32 v79, v12, v13 offset1:1
	v_add_co_u32_e32 v12, vcc, s68, v28
	v_add_u32_e32 v83, 0x1080, v56
	s_nop 0
	v_addc_co_u32_e32 v13, vcc, 0, v29, vcc
	s_mov_b32 s68, 0x1e0000
	ds_write2_b32 v83, v16, v17 offset1:1
	v_add_co_u32_e32 v16, vcc, s68, v28
	v_add_u32_e32 v87, 0x14a0, v56
	s_nop 0
	v_addc_co_u32_e32 v17, vcc, 0, v29, vcc
	s_mov_b32 s68, 0x208000
	ds_write2_b32 v87, v20, v21 offset1:1
	v_add_co_u32_e32 v20, vcc, s68, v28
	v_add_u32_e32 v91, 0x18c0, v56
	s_nop 0
	v_addc_co_u32_e32 v21, vcc, 0, v29, vcc
	s_mov_b32 s68, 0x230000
	ds_write2_b32 v91, v24, v25 offset1:1
	v_add_co_u32_e32 v24, vcc, s68, v28
	s_mov_b32 s68, 0x258000
	s_nop 0
	v_addc_co_u32_e32 v25, vcc, 0, v29, vcc
	v_add_co_u32_e32 v28, vcc, s68, v28
	v_lshl_add_u64 v[120:121], v[116:117], 0, s[52:53]
	s_nop 0
	v_addc_co_u32_e32 v29, vcc, 0, v29, vcc
	v_add_u32_e32 v73, 0x428, v56
	v_add_u32_e32 v77, 0x848, v56
	v_add_u32_e32 v81, 0xc68, v56
	v_add_u32_e32 v85, 0x1088, v56
	v_add_u32_e32 v89, 0x14a8, v56
	v_add_u32_e32 v136, 0x18c8, v56
	v_add_u32_e32 v138, 0x1ce8, v56
	v_add_co_u32_e32 v34, vcc, s58, v120
	ds_write2_b32 v73, v6, v7 offset1:1
	ds_write2_b32 v77, v10, v11 offset1:1
	ds_write2_b32 v81, v14, v15 offset1:1
	ds_write2_b32 v85, v18, v19 offset1:1
	ds_write2_b32 v89, v22, v23 offset1:1
	ds_write2_b32 v136, v26, v27 offset1:1
	ds_write2_b32 v138, v30, v31 offset1:1
	v_addc_co_u32_e32 v35, vcc, 0, v121, vcc
	global_load_dwordx4 v[0:3], v[0:1], off nt
	v_lshl_add_u64 v[32:33], v[120:121], 0, s[16:17]
	global_load_dwordx4 v[4:7], v[4:5], off nt
	v_lshl_add_u64 v[122:123], v[120:121], 0, s[22:23]
	global_load_dwordx4 v[8:11], v[8:9], off nt
	v_lshl_add_u64 v[124:125], v[108:109], 0, v[58:59]
	global_load_dwordx4 v[12:15], v[12:13], off nt
	s_add_u32 s52, s52, 0x100
	global_load_dwordx4 v[16:19], v[16:17], off nt
	s_addc_u32 s53, s53, 0
	global_load_dwordx4 v[20:23], v[20:21], off nt
	v_lshl_add_u64 v[108:109], v[108:109], 0, s[14:15]
	global_load_dwordx4 v[24:27], v[24:25], off nt
	v_lshl_add_u64 v[118:119], v[118:119], 0, s[24:25]
	global_load_dwordx4 v[28:31], v[28:29], off nt
	s_nop 0
	global_load_dwordx4 v[44:47], v[34:35], off
	global_load_dwordx4 v[36:39], v[32:33], off offset:16
	v_add_co_u32_e32 v34, vcc, s59, v120
	v_lshl_add_u64 v[32:33], v[120:121], 0, s[18:19]
	s_nop 0
	v_addc_co_u32_e32 v35, vcc, 0, v121, vcc
	global_load_dwordx4 v[48:51], v[34:35], off
	global_load_dwordx4 v[126:129], v[32:33], off offset:16
	v_add_co_u32_e32 v34, vcc, s60, v120
	v_lshl_add_u64 v[32:33], v[120:121], 0, s[20:21]
	s_nop 0
	v_addc_co_u32_e32 v35, vcc, 0, v121, vcc
	v_add_co_u32_e32 v120, vcc, s61, v120
	global_load_dwordx4 v[40:43], v[34:35], off
	s_nop 0
	global_load_dwordx4 v[32:35], v[32:33], off offset:16
	v_addc_co_u32_e32 v121, vcc, 0, v121, vcc
	global_load_dwordx4 v[130:133], v[120:121], off
	global_load_dwordx4 v[154:157], v[122:123], off offset:16
	s_waitcnt lgkmcnt(0)
	ds_read2_b32 v[140:141], v146 offset0:33 offset1:41
	ds_read2_b32 v[158:159], v146 offset1:8
	ds_read2_b32 v[160:161], v146 offset0:66 offset1:74
	ds_read2_b32 v[162:163], v146 offset0:99 offset1:107
	ds_read2_b32 v[164:165], v146 offset0:132 offset1:140
	ds_read2_b32 v[166:167], v146 offset0:165 offset1:173
	ds_read2_b32 v[168:169], v146 offset0:198 offset1:206
	ds_read2_b32 v[170:171], v146 offset0:231 offset1:239
	s_cmpk_eq_i32 s52, 0x1f00
	s_waitcnt lgkmcnt(6)
	v_cvt_pk_bf16_f32 v120, v158, v140
	s_waitcnt lgkmcnt(4)
	v_cvt_pk_bf16_f32 v121, v160, v162
	s_waitcnt lgkmcnt(2)
	v_cvt_pk_bf16_f32 v122, v164, v166
	s_waitcnt lgkmcnt(0)
	v_cvt_pk_bf16_f32 v123, v168, v170
	global_store_dwordx4 v[124:125], v[120:123], off nt
	v_and_b32_e32 v135, 0xffff0000, v120
	v_lshlrev_b32_e32 v134, 16, v120
	v_and_b32_e32 v173, 0xffff0000, v121
	v_lshlrev_b32_e32 v172, 16, v121
	v_and_b32_e32 v177, 0xffff0000, v123
	v_lshlrev_b32_e32 v176, 16, v123
	v_and_b32_e32 v175, 0xffff0000, v122
	v_lshlrev_b32_e32 v174, 16, v122
	s_waitcnt vmcnt(8)
	v_mov_b32_e32 v121, v45
	v_mov_b32_e32 v123, v47
	s_waitcnt vmcnt(7)
	v_mov_b32_e32 v125, v37
	s_waitcnt vmcnt(6)
	v_mov_b32_e32 v45, v49
	v_mov_b32_e32 v47, v51
	v_mov_b32_e32 v120, v48
	v_pk_mul_f32 v[48:49], v[44:45], v[134:135]
	v_mov_b32_e32 v122, v50
	v_pk_mul_f32 v[50:51], v[46:47], v[172:173]
	v_pk_fma_f32 v[48:49], v[120:121], v[134:135], v[48:49] op_sel:[0,0,1] op_sel_hi:[1,1,0]
	v_pk_fma_f32 v[50:51], v[122:123], v[172:173], v[50:51] op_sel:[0,0,1] op_sel_hi:[1,1,0]
	s_waitcnt vmcnt(5)
	v_mov_b32_e32 v37, v127
	v_pk_add_f32 v[48:49], v[48:49], v[50:51]
	v_mov_b32_e32 v124, v126
	v_pk_mul_f32 v[50:51], v[36:37], v[174:175]
	v_mov_b32_e32 v127, v39
	v_pk_fma_f32 v[50:51], v[124:125], v[174:175], v[50:51] op_sel:[0,0,1] op_sel_hi:[1,1,0]
	v_mov_b32_e32 v39, v129
	v_pk_add_f32 v[48:49], v[48:49], v[50:51]
	v_mov_b32_e32 v126, v128
	v_pk_mul_f32 v[50:51], v[38:39], v[176:177]
	s_waitcnt vmcnt(2)
; __device__ __forceinline__ unsigned cvt_pk_bf16_c(float lo, float hi) { const f32x2_t v = {lo, hi}; return __builtin_bit_cast(unsigned, __builtin_convertvector(v, bf16x2_t)); }
; #define LAS __attribute__((address_space(3)))
; template <bool WITH_SW, bool TILED = false> __device__ __forceinline__ void wt_col_item(const float* W, int N, bf16_t* WT, int Kst, int kb0, int kb1, bool upmap, LAS float* scr, int nb, int lane, const float* shift, float* SWo) {
;     ...
;         for (int j = 0; j < 4; ++j) { const int n = (lane >> 3) + 8 * j; const LAS float* sp = scr + (8 * c) * 33 + n;
;             u32x4 o; o.x = cvt_pk_bf16_c(sp[0 * 33], sp[1 * 33]); o.y = cvt_pk_bf16_c(sp[2 * 33], sp[3 * 33]); o.z = cvt_pk_bf16_c(sp[4 * 33], sp[5 * 33]); o.w = cvt_pk_bf16_c(sp[6 * 33], sp[7 * 33]);
;             if constexpr (TILED) __builtin_nontemporal_store(o, (u32x4*)(WT + (size_t)((r0 + n) >> 8) * ((size_t)256 * Kst) + (size_t)(k0 >> 6) * (256 * 64) + ((r0 + n) & 255) * 64 + 8 * c));
;             else *(u32x4*)(WT + (size_t)(r0 + n) * Kst + k0 + 8 * c) = o;
;             if constexpr (WITH_SW) { float wv[8]; unpack8(o, wv);
; #pragma unroll
;                 for (int b = 0; b < NB; ++b) a[j][b] += (s0[b].x * wv[0] + s0[b].y * wv[1]) + (s0[b].z * wv[2] + s0[b].w * wv[3]) + (s1[b].x * wv[4] + s1[b].y * wv[5]) + (s1[b].z * wv[6] + s1[b].w * wv[7]); } }
	v_mov_b32_e32 v128, v130
	v_pk_fma_f32 v[50:51], v[126:127], v[176:177], v[50:51] op_sel:[0,0,1] op_sel_hi:[1,1,0]
	v_mov_b32_e32 v129, v41
	v_pk_add_f32 v[48:49], v[48:49], v[50:51]
	v_mov_b32_e32 v41, v131
	v_mov_b32_e32 v130, v132
	v_mov_b32_e32 v131, v43
	v_pk_add_f32 v[106:107], v[106:107], v[48:49]
	v_pk_mul_f32 v[48:49], v[128:129], v[134:135]
	v_pk_mul_f32 v[50:51], v[130:131], v[172:173]
	v_mov_b32_e32 v43, v133
	v_pk_fma_f32 v[48:49], v[40:41], v[134:135], v[48:49] op_sel:[0,0,1] op_sel_hi:[1,1,0]
	v_pk_fma_f32 v[50:51], v[42:43], v[172:173], v[50:51] op_sel:[0,0,1] op_sel_hi:[1,1,0]
	s_waitcnt vmcnt(1)
	v_mov_b32_e32 v132, v154
	v_mov_b32_e32 v133, v33
	v_pk_add_f32 v[48:49], v[48:49], v[50:51]
	v_pk_mul_f32 v[50:51], v[132:133], v[174:175]
	v_mov_b32_e32 v33, v155
	v_pk_fma_f32 v[50:51], v[32:33], v[174:175], v[50:51] op_sel:[0,0,1] op_sel_hi:[1,1,0]
	v_mov_b32_e32 v134, v156
	v_mov_b32_e32 v135, v35
	v_pk_add_f32 v[48:49], v[48:49], v[50:51]
	v_pk_mul_f32 v[50:51], v[134:135], v[176:177]
	v_mov_b32_e32 v35, v157
	v_pk_fma_f32 v[50:51], v[34:35], v[176:177], v[50:51] op_sel:[0,0,1] op_sel_hi:[1,1,0]
	s_nop 0
	v_pk_add_f32 v[48:49], v[48:49], v[50:51]
	v_cvt_pk_bf16_f32 v50, v165, v167
	v_pk_add_f32 v[104:105], v[104:105], v[48:49]
	v_cvt_pk_bf16_f32 v48, v159, v141
	v_cvt_pk_bf16_f32 v49, v161, v163
	v_cvt_pk_bf16_f32 v51, v169, v171
	v_lshl_add_u64 v[140:141], v[110:111], 0, v[58:59]
	global_store_dwordx4 v[140:141], v[48:51], off nt
	v_and_b32_e32 v141, 0xffff0000, v48
	v_lshlrev_b32_e32 v140, 16, v48
	v_and_b32_e32 v155, 0xffff0000, v49
	v_lshlrev_b32_e32 v154, 16, v49
	v_and_b32_e32 v49, 0xffff0000, v50
	v_lshlrev_b32_e32 v48, 16, v50
	v_and_b32_e32 v157, 0xffff0000, v51
	v_lshlrev_b32_e32 v156, 16, v51
	v_pk_mul_f32 v[50:51], v[44:45], v[140:141]
	v_pk_mul_f32 v[158:159], v[46:47], v[154:155]
	v_pk_fma_f32 v[50:51], v[120:121], v[140:141], v[50:51] op_sel:[0,0,1] op_sel_hi:[1,1,0]
	v_pk_fma_f32 v[158:159], v[122:123], v[154:155], v[158:159] op_sel:[0,0,1] op_sel_hi:[1,1,0]
	v_lshl_add_u64 v[168:169], v[112:113], 0, v[58:59]
	v_pk_add_f32 v[50:51], v[50:51], v[158:159]
	v_pk_mul_f32 v[158:159], v[36:37], v[48:49]
	v_lshl_add_u64 v[110:111], v[110:111], 0, s[14:15]
	v_pk_fma_f32 v[158:159], v[124:125], v[48:49], v[158:159] op_sel:[0,0,1] op_sel_hi:[1,1,0]
	v_lshl_add_u64 v[112:113], v[112:113], 0, s[14:15]
	v_pk_add_f32 v[50:51], v[50:51], v[158:159]
	v_pk_mul_f32 v[158:159], v[38:39], v[156:157]
	s_nop 0
	v_pk_fma_f32 v[158:159], v[126:127], v[156:157], v[158:159] op_sel:[0,0,1] op_sel_hi:[1,1,0]
	s_nop 0
	v_pk_add_f32 v[50:51], v[50:51], v[158:159]
	s_nop 0
	v_pk_add_f32 v[102:103], v[102:103], v[50:51]
	v_pk_mul_f32 v[50:51], v[128:129], v[140:141]
	s_nop 0
	v_pk_fma_f32 v[50:51], v[40:41], v[140:141], v[50:51] op_sel:[0,0,1] op_sel_hi:[1,1,0]
	v_pk_mul_f32 v[140:141], v[130:131], v[154:155]
	s_nop 0
	v_pk_fma_f32 v[140:141], v[42:43], v[154:155], v[140:141] op_sel:[0,0,1] op_sel_hi:[1,1,0]
	s_nop 0
	v_pk_add_f32 v[50:51], v[50:51], v[140:141]
	v_pk_mul_f32 v[140:141], v[132:133], v[48:49]
	s_nop 0
	v_pk_fma_f32 v[48:49], v[32:33], v[48:49], v[140:141] op_sel:[0,0,1] op_sel_hi:[1,1,0]
	ds_read2_b32 v[140:141], v146 offset0:16 offset1:24
	ds_read2_b32 v[154:155], v146 offset0:49 offset1:57
	v_pk_add_f32 v[48:49], v[50:51], v[48:49]
	v_pk_mul_f32 v[50:51], v[134:135], v[156:157]
	s_nop 0
	v_pk_fma_f32 v[50:51], v[34:35], v[156:157], v[50:51] op_sel:[0,0,1] op_sel_hi:[1,1,0]
	ds_read2_b32 v[156:157], v146 offset0:82 offset1:90
	ds_read2_b32 v[158:159], v146 offset0:115 offset1:123
	ds_read2_b32 v[160:161], v146 offset0:148 offset1:156
	ds_read2_b32 v[162:163], v146 offset0:181 offset1:189
	ds_read2_b32 v[164:165], v146 offset0:214 offset1:222
	ds_read2_b32 v[166:167], v146 offset0:247 offset1:255
	v_pk_add_f32 v[48:49], v[48:49], v[50:51]
	s_waitcnt lgkmcnt(2)
	v_cvt_pk_bf16_f32 v50, v160, v162
	v_pk_add_f32 v[100:101], v[100:101], v[48:49]
	v_cvt_pk_bf16_f32 v48, v140, v154
	v_cvt_pk_bf16_f32 v49, v156, v158
	s_waitcnt lgkmcnt(0)
	v_cvt_pk_bf16_f32 v51, v164, v166
	global_store_dwordx4 v[168:169], v[48:51], off nt
	v_and_b32_e32 v169, 0xffff0000, v48
	v_lshlrev_b32_e32 v168, 16, v48
	v_and_b32_e32 v171, 0xffff0000, v49
	v_lshlrev_b32_e32 v170, 16, v49
	v_and_b32_e32 v49, 0xffff0000, v50
	v_lshlrev_b32_e32 v48, 16, v50
	v_and_b32_e32 v173, 0xffff0000, v51
	v_lshlrev_b32_e32 v172, 16, v51
	v_pk_mul_f32 v[50:51], v[44:45], v[168:169]
	v_pk_mul_f32 v[174:175], v[46:47], v[170:171]
	v_pk_fma_f32 v[50:51], v[120:121], v[168:169], v[50:51] op_sel:[0,0,1] op_sel_hi:[1,1,0]
	v_pk_fma_f32 v[174:175], v[122:123], v[170:171], v[174:175] op_sel:[0,0,1] op_sel_hi:[1,1,0]
	s_nop 0
	v_pk_add_f32 v[50:51], v[50:51], v[174:175]
	v_pk_mul_f32 v[174:175], v[36:37], v[48:49]
	s_nop 0
	v_pk_fma_f32 v[174:175], v[124:125], v[48:49], v[174:175] op_sel:[0,0,1] op_sel_hi:[1,1,0]
	s_nop 0
	v_pk_add_f32 v[50:51], v[50:51], v[174:175]
	v_pk_mul_f32 v[174:175], v[38:39], v[172:173]
	s_nop 0
	v_pk_fma_f32 v[174:175], v[126:127], v[172:173], v[174:175] op_sel:[0,0,1] op_sel_hi:[1,1,0]
	s_nop 0
	v_pk_add_f32 v[50:51], v[50:51], v[174:175]
	s_nop 0
	v_pk_add_f32 v[98:99], v[98:99], v[50:51]
	v_pk_mul_f32 v[50:51], v[128:129], v[168:169]
	s_nop 0
	v_pk_fma_f32 v[50:51], v[40:41], v[168:169], v[50:51] op_sel:[0,0,1] op_sel_hi:[1,1,0]
	v_pk_mul_f32 v[168:169], v[130:131], v[170:171]
	s_nop 0
	v_pk_fma_f32 v[168:169], v[42:43], v[170:171], v[168:169] op_sel:[0,0,1] op_sel_hi:[1,1,0]
	s_nop 0
	v_pk_add_f32 v[50:51], v[50:51], v[168:169]
	v_pk_mul_f32 v[168:169], v[132:133], v[48:49]
	s_nop 0
	v_pk_fma_f32 v[48:49], v[32:33], v[48:49], v[168:169] op_sel:[0,0,1] op_sel_hi:[1,1,0]
; __device__ __forceinline__ unsigned cvt_pk_bf16_c(float lo, float hi) { const f32x2_t v = {lo, hi}; return __builtin_bit_cast(unsigned, __builtin_convertvector(v, bf16x2_t)); }
; #define LAS __attribute__((address_space(3)))
; template <bool WITH_SW, bool TILED = false> __device__ __forceinline__ void wt_col_item(const float* W, int N, bf16_t* WT, int Kst, int kb0, int kb1, bool upmap, LAS float* scr, int nb, int lane, const float* shift, float* SWo) {
;     ...
;         for (int j = 0; j < 4; ++j) { const int n = (lane >> 3) + 8 * j; const LAS float* sp = scr + (8 * c) * 33 + n;
;             u32x4 o; o.x = cvt_pk_bf16_c(sp[0 * 33], sp[1 * 33]); o.y = cvt_pk_bf16_c(sp[2 * 33], sp[3 * 33]); o.z = cvt_pk_bf16_c(sp[4 * 33], sp[5 * 33]); o.w = cvt_pk_bf16_c(sp[6 * 33], sp[7 * 33]);
;             if constexpr (TILED) __builtin_nontemporal_store(o, (u32x4*)(WT + (size_t)((r0 + n) >> 8) * ((size_t)256 * Kst) + (size_t)(k0 >> 6) * (256 * 64) + ((r0 + n) & 255) * 64 + 8 * c));
;             else *(u32x4*)(WT + (size_t)(r0 + n) * Kst + k0 + 8 * c) = o;
;             if constexpr (WITH_SW) { float wv[8]; unpack8(o, wv);
; #pragma unroll
;                 for (int b = 0; b < NB; ++b) a[j][b] += (s0[b].x * wv[0] + s0[b].y * wv[1]) + (s0[b].z * wv[2] + s0[b].w * wv[3]) + (s1[b].x * wv[4] + s1[b].y * wv[5]) + (s1[b].z * wv[6] + s1[b].w * wv[7]); } }
;         asm volatile("s_waitcnt lgkmcnt(0)" ::: "memory");
;     }
	s_nop 0
	v_pk_add_f32 v[48:49], v[50:51], v[48:49]
	v_pk_mul_f32 v[50:51], v[134:135], v[172:173]
	s_nop 0
	v_pk_fma_f32 v[50:51], v[34:35], v[172:173], v[50:51] op_sel:[0,0,1] op_sel_hi:[1,1,0]
	s_nop 0
	v_pk_add_f32 v[48:49], v[48:49], v[50:51]
	v_cvt_pk_bf16_f32 v50, v161, v163
	v_pk_add_f32 v[96:97], v[96:97], v[48:49]
	v_cvt_pk_bf16_f32 v48, v141, v155
	v_cvt_pk_bf16_f32 v49, v157, v159
	v_cvt_pk_bf16_f32 v51, v165, v167
	v_lshl_add_u64 v[140:141], v[114:115], 0, v[58:59]
	global_store_dwordx4 v[140:141], v[48:51], off nt
	v_and_b32_e32 v141, 0xffff0000, v48
	v_lshlrev_b32_e32 v140, 16, v48
	v_and_b32_e32 v155, 0xffff0000, v49
	v_lshlrev_b32_e32 v154, 16, v49
	v_and_b32_e32 v49, 0xffff0000, v50
	v_lshlrev_b32_e32 v48, 16, v50
	v_pk_mul_f32 v[44:45], v[44:45], v[140:141]
	v_pk_mul_f32 v[46:47], v[46:47], v[154:155]
	v_and_b32_e32 v157, 0xffff0000, v51
	v_lshlrev_b32_e32 v156, 16, v51
	v_pk_fma_f32 v[44:45], v[120:121], v[140:141], v[44:45] op_sel:[0,0,1] op_sel_hi:[1,1,0]
	v_pk_fma_f32 v[46:47], v[122:123], v[154:155], v[46:47] op_sel:[0,0,1] op_sel_hi:[1,1,0]
	v_pk_mul_f32 v[36:37], v[36:37], v[48:49]
	v_pk_add_f32 v[44:45], v[44:45], v[46:47]
	v_pk_fma_f32 v[36:37], v[124:125], v[48:49], v[36:37] op_sel:[0,0,1] op_sel_hi:[1,1,0]
	v_pk_mul_f32 v[38:39], v[38:39], v[156:157]
	v_pk_add_f32 v[36:37], v[44:45], v[36:37]
	v_pk_fma_f32 v[38:39], v[126:127], v[156:157], v[38:39] op_sel:[0,0,1] op_sel_hi:[1,1,0]
	v_lshl_add_u64 v[114:115], v[114:115], 0, s[14:15]
	v_pk_add_f32 v[36:37], v[36:37], v[38:39]
	v_pk_mul_f32 v[38:39], v[130:131], v[154:155]
	v_pk_add_f32 v[94:95], v[94:95], v[36:37]
	v_pk_mul_f32 v[36:37], v[128:129], v[140:141]
	v_pk_fma_f32 v[38:39], v[42:43], v[154:155], v[38:39] op_sel:[0,0,1] op_sel_hi:[1,1,0]
	v_pk_fma_f32 v[36:37], v[40:41], v[140:141], v[36:37] op_sel:[0,0,1] op_sel_hi:[1,1,0]
	s_nop 0
	v_pk_add_f32 v[36:37], v[36:37], v[38:39]
	v_pk_mul_f32 v[38:39], v[132:133], v[48:49]
	s_nop 0
	v_pk_fma_f32 v[32:33], v[32:33], v[48:49], v[38:39] op_sel:[0,0,1] op_sel_hi:[1,1,0]
	s_nop 0
	v_pk_add_f32 v[32:33], v[36:37], v[32:33]
	v_pk_mul_f32 v[36:37], v[134:135], v[156:157]
	s_nop 0
	v_pk_fma_f32 v[34:35], v[34:35], v[156:157], v[36:37] op_sel:[0,0,1] op_sel_hi:[1,1,0]
	s_nop 0
	v_pk_add_f32 v[32:33], v[32:33], v[34:35]
	s_nop 0
	v_pk_add_f32 v[92:93], v[92:93], v[32:33]
	s_cbranch_scc0 .LBB0_201
; #define LAS __attribute__((address_space(3)))
; template <bool WITH_SW, bool TILED = false> __device__ __forceinline__ void wt_col_item(const float* W, int N, bf16_t* WT, int Kst, int kb0, int kb1, bool upmap, LAS float* scr, int nb, int lane, const float* shift, float* SWo) {
;     ...
;     for (int kb = kb0; kb < kb1; ++kb) { const int k0 = 64 * kb;
; #pragma unroll
;         for (int i = 0; i < 8; ++i) { LAS float* d = scr + ((lane >> 3) + 8 * i) * 33 + 4 * (lane & 7); d[0] = t[i].x; d[1] = t[i].y; d[2] = t[i].z; d[3] = t[i].w; }
;         if (kb + 1 < kb1) {
; #pragma unroll
;             for (int i = 0; i < 8; ++i) t[i] = __builtin_nontemporal_load((const f32x4*)(W + (size_t)(k0 + 64 + (lane >> 3) + 8 * i) * N + n0 + 4 * (lane & 7))); }
;         f32x4 s0[NB], s1[NB];
;         if constexpr (WITH_SW) {
; #pragma unroll
;             for (int b = 0; b < NB; ++b) { s0[b] = *(const f32x4*)(shift + (size_t)b * 6 * D + k0 + 8 * c); s1[b] = *(const f32x4*)(shift + (size_t)b * 6 * D + k0 + 8 * c + 4); } }
;         asm volatile("s_waitcnt lgkmcnt(0)" ::: "memory");
; #pragma unroll
;         for (int j = 0; j < 4; ++j) { const int n = (lane >> 3) + 8 * j; const LAS float* sp = scr + (8 * c) * 33 + n;
;             u32x4 o; o.x = cvt_pk_bf16_c(sp[0 * 33], sp[1 * 33]); o.y = cvt_pk_bf16_c(sp[2 * 33], sp[3 * 33]); o.z = cvt_pk_bf16_c(sp[4 * 33], sp[5 * 33]); o.w = cvt_pk_bf16_c(sp[6 * 33], sp[7 * 33]);
;             if constexpr (TILED) __builtin_nontemporal_store(o, (u32x4*)(WT + (size_t)((r0 + n) >> 8) * ((size_t)256 * Kst) + (size_t)(k0 >> 6) * (256 * 64) + ((r0 + n) & 255) * 64 + 8 * c));
;             else *(u32x4*)(WT + (size_t)(r0 + n) * Kst + k0 + 8 * c) = o;
;             if constexpr (WITH_SW) { float wv[8]; unpack8(o, wv);
; #pragma unroll
;                 for (int b = 0; b < NB; ++b) a[j][b] += (s0[b].x * wv[0] + s0[b].y * wv[1]) + (s0[b].z * wv[2] + s0[b].w * wv[3]) + (s1[b].x * wv[4] + s1[b].y * wv[5]) + (s1[b].z * wv[6] + s1[b].w * wv[7]); } }
;         asm volatile("s_waitcnt lgkmcnt(0)" ::: "memory");
;     }
;     if constexpr (WITH_SW) {
; #pragma unroll
;         for (int j = 0; j < 4; ++j)
; #pragma unroll
;             for (int b = 0; b < NB; ++b) { float v = a[j][b]; v += bperm(v, lane ^ 1); v += bperm(v, lane ^ 2); v += bperm(v, lane ^ 4);
;                 if (c == 0) SWo[(size_t)b * N + r0 + (lane >> 3) + 8 * j] = v; } }
	v_lshl_add_u64 v[32:33], v[62:63], 0, s[36:37]
	ds_write2_b32 v56, v0, v1 offset1:1
	ds_write2_b32 v56, v2, v3 offset0:2 offset1:3
	ds_write2_b32 v71, v4, v5 offset1:1
	ds_write2_b32 v73, v6, v7 offset1:1
	ds_write2_b32 v75, v8, v9 offset1:1
	ds_write2_b32 v77, v10, v11 offset1:1
	ds_write2_b32 v79, v12, v13 offset1:1
	ds_write2_b32 v81, v14, v15 offset1:1
	ds_write2_b32 v83, v16, v17 offset1:1
	ds_write2_b32 v85, v18, v19 offset1:1
	ds_write2_b32 v87, v20, v21 offset1:1
	ds_write2_b32 v89, v22, v23 offset1:1
	ds_write2_b32 v91, v24, v25 offset1:1
	ds_write2_b32 v136, v26, v27 offset1:1
	ds_write2_b32 v137, v28, v29 offset1:1
	ds_write2_b32 v138, v30, v31 offset1:1
	v_add_co_u32_e32 v0, vcc, s62, v32
	v_lshl_add_u64 v[4:5], v[32:33], 0, s[26:27]
	s_nop 0
	v_addc_co_u32_e32 v1, vcc, 0, v33, vcc
	global_load_dwordx4 v[0:3], v[0:1], off offset:3840
	s_nop 0
	global_load_dwordx4 v[8:11], v[4:5], off offset:16
	v_add_co_u32_e32 v6, vcc, s63, v32
	v_lshl_add_u64 v[4:5], v[32:33], 0, s[28:29]
	s_nop 0
	v_addc_co_u32_e32 v7, vcc, 0, v33, vcc
	global_load_dwordx4 v[28:31], v[6:7], off offset:3840
	global_load_dwordx4 v[24:27], v[4:5], off offset:16
	v_add_co_u32_e32 v6, vcc, s64, v32
	v_lshl_add_u64 v[4:5], v[32:33], 0, s[30:31]
	s_nop 0
	v_addc_co_u32_e32 v7, vcc, 0, v33, vcc
	global_load_dwordx4 v[20:23], v[6:7], off offset:3840
	global_load_dwordx4 v[16:19], v[4:5], off offset:16
	v_add_co_u32_e32 v6, vcc, s65, v32
	v_lshl_add_u64 v[4:5], v[32:33], 0, s[34:35]
	s_nop 0
	v_addc_co_u32_e32 v7, vcc, 0, v33, vcc
	global_load_dwordx4 v[12:15], v[6:7], off offset:3840
	s_nop 0
	global_load_dwordx4 v[4:7], v[4:5], off offset:16
	s_add_u32 s47, s49, s47
	s_waitcnt lgkmcnt(0)
	s_addc_u32 s52, s50, s10
	s_mul_hi_i32 s36, s67, 0x14000
	s_mul_i32 s67, s67, 0x14000
	ds_read2_b32 v[36:37], v146 offset0:33 offset1:41
	ds_read2_b32 v[38:39], v146 offset1:8
	s_add_u32 s10, s51, s67
	v_or_b32_e32 v46, s46, v54
	v_or_b32_e32 v114, s46, v61
	v_or_b32_e32 v118, s46, v142
	v_or_b32_e32 v120, s46, v143
	s_addc_u32 s46, s54, s36
	ds_read2_b32 v[40:41], v146 offset0:66 offset1:74
	ds_read2_b32 v[42:43], v146 offset0:99 offset1:107
	ds_read2_b32 v[44:45], v146 offset0:132 offset1:140
	ds_read2_b32 v[108:109], v146 offset0:165 offset1:173
	ds_read2_b32 v[110:111], v146 offset0:198 offset1:206
	ds_read2_b32 v[112:113], v146 offset0:231 offset1:239
	s_add_u32 s36, s47, s44
	s_addc_u32 s37, s52, s45
	s_waitcnt lgkmcnt(6)
	v_cvt_pk_bf16_f32 v32, v38, v36
	s_add_u32 s36, s36, 0xf8000
	v_lshlrev_b32_e32 v36, 7, v46
	s_addc_u32 s37, s37, 0
	v_and_b32_e32 v56, 0x7380, v36
	s_waitcnt lgkmcnt(4)
	v_cvt_pk_bf16_f32 v33, v40, v42
	v_lshl_add_u64 v[46:47], s[36:37], 0, v[56:57]
	v_lshlrev_b32_e32 v56, 1, v60
	s_waitcnt lgkmcnt(2)
	v_cvt_pk_bf16_f32 v34, v44, v108
	s_waitcnt lgkmcnt(0)
	v_cvt_pk_bf16_f32 v35, v110, v112
	v_lshl_add_u64 v[46:47], v[46:47], 0, v[56:57]
	v_and_b32_e32 v73, 0xffff0000, v32
	v_and_b32_e32 v71, 0xffff0000, v33
	global_store_dwordx4 v[46:47], v[32:35], off nt
	v_lshlrev_b32_e32 v50, 16, v32
	v_lshlrev_b32_e32 v49, 16, v33
	v_and_b32_e32 v51, 0xffff0000, v34
	v_lshlrev_b32_e32 v47, 16, v34
	v_and_b32_e32 v48, 0xffff0000, v35
	v_lshlrev_b32_e32 v46, 16, v35
	v_cvt_pk_bf16_f32 v40, v39, v37
	v_cvt_pk_bf16_f32 v41, v41, v43
	v_cvt_pk_bf16_f32 v42, v45, v109
	v_cvt_pk_bf16_f32 v43, v111, v113
	v_mov_b32_e32 v119, v57
	s_waitcnt vmcnt(8)
	v_mul_f32_e32 v32, v1, v73
	v_mul_f32_e32 v33, v3, v71
	v_fmac_f32_e32 v32, v0, v50
	v_fmac_f32_e32 v33, v2, v49
	v_add_f32_e32 v32, v32, v33
	s_waitcnt vmcnt(7)
	v_mul_f32_e32 v33, v9, v51
	v_fmac_f32_e32 v33, v8, v47
	v_add_f32_e32 v32, v32, v33
	v_mul_f32_e32 v33, v11, v48
	v_fmac_f32_e32 v33, v10, v46
	v_add_f32_e32 v32, v32, v33
	v_add_f32_e32 v75, v107, v32
	v_lshlrev_b32_e32 v32, 7, v114
	v_and_b32_e32 v32, 0x7780, v32
	v_mov_b32_e32 v33, v57
	v_lshl_add_u64 v[32:33], s[36:37], 0, v[32:33]
	v_lshl_add_u64 v[32:33], v[32:33], 0, v[56:57]
	global_store_dwordx4 v[32:33], v[40:43], off nt
	ds_read2_b32 v[32:33], v146 offset0:16 offset1:24
	ds_read2_b32 v[34:35], v146 offset0:49 offset1:57
	ds_read2_b32 v[44:45], v146 offset0:82 offset1:90
	ds_read2_b32 v[108:109], v146 offset0:115 offset1:123
	ds_read2_b32 v[110:111], v146 offset0:148 offset1:156
	ds_read2_b32 v[112:113], v146 offset0:181 offset1:189
	ds_read2_b32 v[114:115], v146 offset0:214 offset1:222
	ds_read2_b32 v[116:117], v146 offset0:247 offset1:255
	s_waitcnt lgkmcnt(6)
	v_cvt_pk_bf16_f32 v36, v32, v34
	s_waitcnt lgkmcnt(4)
	v_cvt_pk_bf16_f32 v37, v44, v108
	v_lshlrev_b32_e32 v32, 7, v118
	v_lshlrev_b32_e32 v44, 7, v120
	v_and_b32_e32 v118, 0x7b80, v32
	v_cvt_pk_bf16_f32 v32, v33, v35
	v_cvt_pk_bf16_f32 v33, v45, v109
	v_and_b32_e32 v44, 0x7f80, v44
	v_mov_b32_e32 v45, v57
	v_lshl_add_u64 v[118:119], s[36:37], 0, v[118:119]
	v_lshl_add_u64 v[44:45], s[36:37], 0, v[44:45]
	s_add_u32 s36, s10, s42
	s_waitcnt lgkmcnt(2)
	v_cvt_pk_bf16_f32 v38, v110, v112
	s_waitcnt lgkmcnt(0)
	v_cvt_pk_bf16_f32 v39, v114, v116
	v_lshl_add_u64 v[118:119], v[118:119], 0, v[56:57]
	v_cvt_pk_bf16_f32 v34, v111, v113
	v_cvt_pk_bf16_f32 v35, v115, v117
	v_lshl_add_u64 v[44:45], v[44:45], 0, v[56:57]
	s_addc_u32 s37, s46, s43
	v_lshlrev_b32_e32 v56, 2, v54
	global_store_dwordx4 v[118:119], v[36:39], off nt
	global_store_dwordx4 v[44:45], v[32:35], off nt
	v_lshl_add_u64 v[44:45], s[36:37], 0, v[56:57]
	ds_bpermute_b32 v56, v147, v75
	s_waitcnt lgkmcnt(0)
	v_add_f32_e32 v56, v75, v56
	ds_bpermute_b32 v75, v148, v56
	s_waitcnt lgkmcnt(0)
	v_add_f32_e32 v56, v56, v75
	ds_bpermute_b32 v75, v149, v56
	s_and_saveexec_b64 s[36:37], s[0:1]
	s_cbranch_execz .LBB0_204
	s_waitcnt lgkmcnt(0)
	v_add_f32_e32 v56, v56, v75
	global_store_dword v[44:45], v56, off

; template <class Ord> __device__ __forceinline__ void hgrn_h1(LAS unsigned char* lds, const _Float16* LF, const bf16_t* V, bf16_t* DS, float* DEC, const Ord& O, int tid) {
;     ...
;         asm volatile("s_waitcnt lgkmcnt(0)" ::: "memory"); __syncthreads();
;         if (nx >= 0) {
;             const int bh = nx >> 6, n = nx & 63; const size_t row0 = (size_t)(bh >> 3) * SEQ + (size_t)n * CH; const _Float16* lfc = LF + row0 * DH + (bh & 7) * 128; const bf16_t* vc = V + row0 * DH + (bh & 7) * 128;
; #pragma unroll
;             for (int j = 0; j < 4; ++j) { const int c = tg + 256 * j; lc[j] = *(const f16x8_t*)(lfc + (size_t)(c >> 4) * DH + (c & 15) * 8); vr[j] = *(const u32x4*)(vc + (size_t)(c >> 4) * DH + (c & 15) * 8); } }
.LBB0_644:
	s_waitcnt lgkmcnt(0)
	s_cmp_lt_i32 s20, 0
	s_barrier
	s_cbranch_scc1 .LBB0_646
	s_lshr_b32 s22, s20, 9
	s_mov_b32 s23, s45
	s_lshl_b32 s21, s20, 17
	s_and_b32 s21, s21, 0x7e0000
	s_lshl_b64 s[22:23], s[22:23], 23
	s_or_b32 s21, s22, s21
	s_add_u32 s22, s12, s21
	s_addc_u32 s25, s13, s23
	s_lshl_b32 s24, s20, 2
	s_and_b32 s26, s24, 0x700
	s_add_u32 s24, s22, s26
	s_addc_u32 s25, s25, 0
	s_add_u32 s21, s10, s21
	s_addc_u32 s23, s11, s23
	s_add_u32 s22, s21, s26
	v_lshlrev_b32_e32 v0, 4, v79
	s_addc_u32 s23, s23, 0
	v_and_b32_e32 v0, 0xf0, v0
	v_ashrrev_i32_e32 v41, 31, v40
	v_ashrrev_i32_e32 v39, 31, v38
	v_ashrrev_i32_e32 v37, 31, v36
	v_ashrrev_i32_e32 v35, 31, v34
	s_waitcnt vmcnt(0)
	v_lshl_add_u64 v[26:27], s[24:25], 0, v[0:1]
	v_lshl_add_u64 v[28:29], s[22:23], 0, v[0:1]
	v_lshlrev_b64 v[2:3], 11, v[40:41]
	v_lshlrev_b64 v[10:11], 11, v[38:39]
	v_lshlrev_b64 v[18:19], 11, v[36:37]
	v_lshlrev_b64 v[30:31], 11, v[34:35]
	v_lshl_add_u64 v[4:5], v[26:27], 0, v[2:3]
	v_lshl_add_u64 v[6:7], v[28:29], 0, v[2:3]
	v_lshl_add_u64 v[12:13], v[26:27], 0, v[10:11]
	v_lshl_add_u64 v[10:11], v[28:29], 0, v[10:11]
	v_lshl_add_u64 v[20:21], v[26:27], 0, v[18:19]
	v_lshl_add_u64 v[18:19], v[28:29], 0, v[18:19]
	v_lshl_add_u64 v[26:27], v[26:27], 0, v[30:31]
	v_lshl_add_u64 v[28:29], v[28:29], 0, v[30:31]
	global_load_dwordx4 v[2:5], v[4:5], off
	s_nop 0
	global_load_dwordx4 v[6:9], v[6:7], off
	s_nop 0
	global_load_dwordx4 v[14:17], v[12:13], off
	s_nop 0
	global_load_dwordx4 v[10:13], v[10:11], off
	s_nop 0
	global_load_dwordx4 v[22:25], v[20:21], off
	s_nop 0
	global_load_dwordx4 v[18:21], v[18:19], off
	s_nop 0
	global_load_dwordx4 v[30:33], v[26:27], off
	s_nop 0
	global_load_dwordx4 v[26:29], v[28:29], off

; __device__ __forceinline__ unsigned cvt_pk_bf16_c(float lo, float hi) { const f32x2_t v = {lo, hi}; return __builtin_bit_cast(unsigned, __builtin_convertvector(v, bf16x2_t)); }
; __device__ __forceinline__ float bperm(float v, int src_lane) { return __int_as_float(__builtin_amdgcn_ds_bpermute(src_lane << 2, __float_as_int(v))); }
; __device__ __forceinline__ void hgrn_h3(LAS unsigned char* lds, const bf16_t* Q, const _Float16* LF, const bf16_t* V, const bf16_t* SG, const bf16_t* SP, const float* gn, bf16_t* YAB, int cid, int G, int tid) {
;     ...
;         asm volatile("s_waitcnt lgkmcnt(0)" ::: "memory"); __syncthreads();
;         if (act) {
; #pragma unroll
;             for (int ps = 0; ps < 2; ++ps) { float lf[2][8], b[2][8], blast; const int d = 16 * (2 * wl + ps) + fr; unsigned kpk[2][8];
; #pragma unroll
;                 for (int ks = 0; ks < 2; ++ks)
; #pragma unroll
;                     for (int i = 0; i < 8; ++i) lf[ks][i] = BM[(32 * ks + 8 * fq + i) * 132 + d];
;                 cumsum_from(lf, fr, fq, b, blast);
; #pragma unroll
;                 for (int ks = 0; ks < 2; ++ks) { const float rend = bperm(b[ks][7], fr + 16 * (fq | 1));
; #pragma unroll
;                     for (int i = 0; i < 8; ++i) { const int s_ = 32 * ks + 8 * fq + i; BM[s_ * 132 + d] = b[ks][i];
;                         const float kv = (1.f - __expf(lf[ks][i])) * __expf(rend - b[ks][i]);
;                         const float ko = __int_as_float(__builtin_amdgcn_update_dpp(0, __float_as_int(kv), 0xB1, 0xf, 0xf, true));
;                         kpk[ks][i] = cvt_pk_bf16_c(kv, ko); } }
.LBB0_977:
	s_waitcnt lgkmcnt(0)
	v_cndmask_b32_e64 v116, 0, 1, s[8:9]
	v_cmp_ne_u32_e64 s[6:7], 1, v116
	s_andn2_b64 vcc, exec, s[8:9]
	s_barrier
	s_cbranch_vccnz .LBB0_983
	v_lshlrev_b32_e32 v138, 2, v117
	v_lshl_or_b32 v118, v225, 6, v138
	v_or_b32_e32 v116, s54, v117
	v_add_u32_e32 v119, 0xc0, v118
	v_bitop3_b32 v139, v118, s84, v243 bitop3:0x6c
	v_and_b32_e32 v118, 1, v223
	v_and_b32_e32 v140, 0xfc, v119
	v_cmp_eq_u32_e32 vcc, 0, v118
	v_lshl_add_u32 v118, v116, 2, s48
	v_mul_lo_u32 v119, v225, s92
	v_lshl_or_b32 v130, v225, 3, 1
	v_add_u32_e32 v137, v118, v119
	v_mul_lo_u32 v119, v130, s62
	v_add_u32_e32 v135, v118, v119
	ds_read_b32 v142, v137
	ds_read2_b32 v[146:147], v135 offset1:132
	v_add_u32_e32 v136, 0x400, v135
	ds_read2_b32 v[128:129], v136 offset0:8 offset1:140
	ds_read_b32 v150, v135 offset:2112
	v_add_u32_e32 v119, 0xa50, v119
	v_add_u32_e32 v134, v118, v119
	ds_read2_b32 v[126:127], v134 offset1:132
	s_waitcnt lgkmcnt(3)
	v_add_f32_e32 v143, v142, v146
	v_add_f32_e32 v144, v143, v147
	s_waitcnt lgkmcnt(2)
	v_add_f32_e32 v145, v144, v128
	v_add_f32_e32 v148, v145, v129
	s_waitcnt lgkmcnt(1)
	v_add_f32_e32 v149, v148, v150
	s_waitcnt lgkmcnt(0)
	v_add_f32_e32 v151, v149, v126
	v_add_f32_e32 v152, v151, v127
	v_add_u32_e32 v133, 0x3400, v134
	ds_bpermute_b32 v161, v140, v152
	ds_read2_b32 v[124:125], v133 offset0:104 offset1:236
	v_add_u32_e32 v157, 0x3800, v134
	ds_read2_b32 v[122:123], v157 offset0:112 offset1:244
	v_add_u32_e32 v141, 0x3c00, v134
	ds_read2_b32 v[120:121], v141 offset0:120 offset1:252
	v_cmp_lt_i32_e64 s[10:11], 0, v225
	v_add_u32_e32 v131, 0x4200, v134
	s_waitcnt lgkmcnt(3)
	v_add_f32_e32 v161, v152, v161
	ds_read2_b32 v[118:119], v131 offset1:132
	s_waitcnt lgkmcnt(3)
	v_add_f32_e32 v153, v124, v125
	v_cndmask_b32_e64 v161, v152, v161, s[10:11]
	s_waitcnt lgkmcnt(2)
	v_add_f32_e32 v154, v153, v122
	ds_bpermute_b32 v162, v139, v161
	v_add_f32_e32 v155, v154, v123
	s_waitcnt lgkmcnt(2)
	v_add_f32_e32 v156, v155, v120
	v_add_f32_e32 v158, v156, v121
	s_waitcnt lgkmcnt(1)
	v_add_f32_e32 v159, v158, v118
	v_cmp_lt_i32_e64 s[8:9], 1, v225
	v_add_f32_e32 v160, v159, v119
	s_waitcnt lgkmcnt(0)
	v_add_f32_e32 v162, v161, v162
	v_cndmask_b32_e64 v161, v161, v162, s[8:9]
	ds_bpermute_b32 v162, v140, v160
	v_lshl_or_b32 v132, v223, 2, 64
	v_mul_f32_e32 v128, 0x3fb8aa3b, v128
	v_mul_f32_e32 v129, 0x3fb8aa3b, v129
	v_mul_f32_e32 v150, 0x3fb8aa3b, v150
	s_waitcnt lgkmcnt(0)
	v_add_f32_e32 v162, v160, v162
	v_cndmask_b32_e64 v162, v160, v162, s[10:11]
	ds_bpermute_b32 v163, v139, v162
	v_mul_f32_e32 v126, 0x3fb8aa3b, v126
	v_mul_f32_e32 v127, 0x3fb8aa3b, v127
	v_mul_f32_e32 v125, 0x3fb8aa3b, v125
	v_mul_f32_e32 v122, 0x3fb8aa3b, v122
	s_waitcnt lgkmcnt(0)
	v_add_f32_e32 v163, v162, v163
	v_cndmask_b32_e64 v162, v162, v163, s[8:9]
	ds_bpermute_b32 v163, v138, v161 offset:192
	v_sub_f32_e32 v161, v161, v152
	v_add_f32_e32 v165, v143, v161
	v_mul_f32_e32 v123, 0x3fb8aa3b, v123
	v_mul_f32_e32 v120, 0x3fb8aa3b, v120
	s_waitcnt lgkmcnt(0)
	v_add_f32_e32 v162, v162, v163
	v_sub_f32_e32 v162, v162, v160
	v_add_f32_e32 v171, v159, v162
	v_add_f32_e32 v159, v152, v161
	v_add_f32_e32 v163, v142, v161
	v_add_f32_e32 v166, v153, v162
	v_add_f32_e32 v153, v144, v161
	v_add_f32_e32 v167, v154, v162
	v_add_f32_e32 v154, v145, v161
	v_add_f32_e32 v168, v155, v162
	v_add_f32_e32 v155, v148, v161
	v_add_f32_e32 v169, v156, v162
	v_add_f32_e32 v156, v149, v161
	v_add_f32_e32 v170, v158, v162
	v_add_f32_e32 v158, v151, v161
	ds_bpermute_b32 v161, v132, v159
	v_add_f32_e32 v160, v160, v162
	v_mul_f32_e32 v144, 0x3fb8aa3b, v146
	ds_write2_b32 v135, v165, v153 offset1:132
	v_mul_f32_e32 v146, 0x3fb8aa3b, v147
	s_waitcnt lgkmcnt(1)
	v_sub_f32_e32 v143, v161, v163
	v_sub_f32_e32 v145, v161, v165
	v_sub_f32_e32 v147, v161, v153
	v_sub_f32_e32 v148, v161, v154
	v_sub_f32_e32 v149, v161, v155
	v_sub_f32_e32 v151, v161, v156
	v_sub_f32_e32 v152, v161, v158
	v_sub_f32_e32 v153, v161, v159
	ds_bpermute_b32 v161, v132, v160
	v_add_f32_e32 v164, v124, v162
	ds_write_b32 v137, v163
	v_mul_f32_e32 v142, 0x3fb8aa3b, v142
	ds_write2_b32 v136, v154, v155 offset0:8 offset1:140
	ds_write_b32 v135, v156 offset:2112
	ds_write2_b32 v134, v158, v159 offset1:132
	v_mul_f32_e32 v124, 0x3fb8aa3b, v124
	s_waitcnt lgkmcnt(4)
; __device__ __forceinline__ unsigned cvt_pk_bf16_c(float lo, float hi) { const f32x2_t v = {lo, hi}; return __builtin_bit_cast(unsigned, __builtin_convertvector(v, bf16x2_t)); }
; __device__ __forceinline__ float bperm(float v, int src_lane) { return __int_as_float(__builtin_amdgcn_ds_bpermute(src_lane << 2, __float_as_int(v))); }
; #define LAS __attribute__((address_space(3)))
; __device__ __forceinline__ void hgrn_h3(LAS unsigned char* lds, const bf16_t* Q, const _Float16* LF, const bf16_t* V, const bf16_t* SG, const bf16_t* SP, const float* gn, bf16_t* YAB, int cid, int G, int tid) {
;     ...
;                 for (int ks = 0; ks < 2; ++ks) { const float rend = bperm(b[ks][7], fr + 16 * (fq | 1));
; #pragma unroll
;                     for (int i = 0; i < 8; ++i) { const int s_ = 32 * ks + 8 * fq + i; BM[s_ * 132 + d] = b[ks][i];
;                         const float kv = (1.f - __expf(lf[ks][i])) * __expf(rend - b[ks][i]);
;                         const float ko = __int_as_float(__builtin_amdgcn_update_dpp(0, __float_as_int(kv), 0xB1, 0xf, 0xf, true));
;                         kpk[ks][i] = cvt_pk_bf16_c(kv, ko); } }
;                 if ((fr & 1) == 0) {
; #pragma unroll
;                     for (int ks = 0; ks < 2; ++ks)
; #pragma unroll
;                         for (int i = 0; i < 8; ++i) *(LAS unsigned*)(KB + ((32 * ks + 8 * fq + i) * 136 + d) * 2) = kpk[ks][i]; } }
	v_sub_f32_e32 v154, v161, v164
	ds_write2_b32 v133, v164, v166 offset0:104 offset1:236
	v_sub_f32_e32 v155, v161, v166
	v_sub_f32_e32 v156, v161, v167
	ds_write2_b32 v157, v167, v168 offset0:112 offset1:244
	v_sub_f32_e32 v157, v161, v168
	v_sub_f32_e32 v158, v161, v169
	ds_write2_b32 v141, v169, v170 offset0:120 offset1:252
	v_mul_f32_e32 v121, 0x3fb8aa3b, v121
	v_sub_f32_e32 v141, v161, v170
	v_mul_f32_e32 v118, 0x3fb8aa3b, v118
	v_sub_f32_e32 v159, v161, v171
	ds_write2_b32 v131, v171, v160 offset1:132
	v_mul_f32_e32 v119, 0x3fb8aa3b, v119
	v_sub_f32_e32 v160, v161, v160
	v_exp_f32_e32 v142, v142
	v_mul_f32_e32 v143, 0x3fb8aa3b, v143
	v_exp_f32_e32 v144, v144
	v_mul_f32_e32 v145, 0x3fb8aa3b, v145
	v_exp_f32_e32 v146, v146
	v_mul_f32_e32 v147, 0x3fb8aa3b, v147
	v_exp_f32_e32 v128, v128
	v_mul_f32_e32 v148, 0x3fb8aa3b, v148
	v_exp_f32_e32 v129, v129
	v_mul_f32_e32 v149, 0x3fb8aa3b, v149
	v_exp_f32_e32 v150, v150
	v_mul_f32_e32 v151, 0x3fb8aa3b, v151
	v_exp_f32_e32 v126, v126
	v_mul_f32_e32 v152, 0x3fb8aa3b, v152
	v_exp_f32_e32 v127, v127
	v_mul_f32_e32 v153, 0x3fb8aa3b, v153
	v_exp_f32_e32 v124, v124
	v_mul_f32_e32 v154, 0x3fb8aa3b, v154
	v_exp_f32_e32 v125, v125
	v_mul_f32_e32 v155, 0x3fb8aa3b, v155
	v_exp_f32_e32 v122, v122
	v_mul_f32_e32 v156, 0x3fb8aa3b, v156
	v_exp_f32_e32 v123, v123
	v_mul_f32_e32 v157, 0x3fb8aa3b, v157
	v_exp_f32_e32 v120, v120
	v_mul_f32_e32 v158, 0x3fb8aa3b, v158
	v_exp_f32_e32 v121, v121
	v_mul_f32_e32 v141, 0x3fb8aa3b, v141
	v_exp_f32_e32 v118, v118
	v_mul_f32_e32 v159, 0x3fb8aa3b, v159
	v_exp_f32_e32 v119, v119
	v_mul_f32_e32 v160, 0x3fb8aa3b, v160
	v_exp_f32_e32 v143, v143
	v_exp_f32_e32 v145, v145
	v_exp_f32_e32 v147, v147
	v_exp_f32_e32 v148, v148
	v_exp_f32_e32 v149, v149
	v_exp_f32_e32 v151, v151
	v_exp_f32_e32 v152, v152
	v_exp_f32_e32 v153, v153
	v_exp_f32_e32 v154, v154
	v_exp_f32_e32 v155, v155
	v_exp_f32_e32 v156, v156
	v_exp_f32_e32 v157, v157
	v_exp_f32_e32 v158, v158
	v_exp_f32_e32 v141, v141
	v_exp_f32_e32 v159, v159
	v_exp_f32_e32 v160, v160
	v_sub_f32_e32 v142, 1.0, v142
	v_sub_f32_e32 v144, 1.0, v144
	v_sub_f32_e32 v146, 1.0, v146
	v_sub_f32_e32 v128, 1.0, v128
	v_sub_f32_e32 v129, 1.0, v129
	v_sub_f32_e32 v150, 1.0, v150
	v_sub_f32_e32 v126, 1.0, v126
	v_sub_f32_e32 v127, 1.0, v127
	v_sub_f32_e32 v124, 1.0, v124
	v_sub_f32_e32 v125, 1.0, v125
	v_sub_f32_e32 v122, 1.0, v122
	v_sub_f32_e32 v123, 1.0, v123
	v_sub_f32_e32 v120, 1.0, v120
	v_sub_f32_e32 v121, 1.0, v121
	v_sub_f32_e32 v118, 1.0, v118
	v_sub_f32_e32 v119, 1.0, v119
	v_mul_f32_e32 v142, v142, v143
	v_mul_f32_e32 v144, v144, v145
	v_mul_f32_e32 v146, v146, v147
	v_mul_f32_e32 v128, v128, v148
	v_mul_f32_e32 v129, v129, v149
	v_mul_f32_e32 v150, v150, v151
	v_mul_f32_e32 v126, v126, v152
	v_mul_f32_e32 v127, v127, v153
	v_mul_f32_e32 v124, v124, v154
	v_mul_f32_e32 v125, v125, v155
	v_mul_f32_e32 v122, v122, v156
	v_mul_f32_e32 v123, v123, v157
	v_mul_f32_e32 v120, v120, v158
	v_mul_f32_e32 v121, v121, v141
	v_mul_f32_e32 v118, v118, v159
	v_mul_f32_e32 v119, v119, v160
	v_mov_b32_dpp v143, v142 quad_perm:[1,0,3,2] row_mask:0xf bank_mask:0xf bound_ctrl:1
	v_mov_b32_dpp v145, v144 quad_perm:[1,0,3,2] row_mask:0xf bank_mask:0xf bound_ctrl:1
	v_mov_b32_dpp v147, v146 quad_perm:[1,0,3,2] row_mask:0xf bank_mask:0xf bound_ctrl:1
	v_mov_b32_dpp v148, v128 quad_perm:[1,0,3,2] row_mask:0xf bank_mask:0xf bound_ctrl:1
	v_mov_b32_dpp v149, v129 quad_perm:[1,0,3,2] row_mask:0xf bank_mask:0xf bound_ctrl:1
	v_mov_b32_dpp v151, v150 quad_perm:[1,0,3,2] row_mask:0xf bank_mask:0xf bound_ctrl:1
	v_mov_b32_dpp v152, v126 quad_perm:[1,0,3,2] row_mask:0xf bank_mask:0xf bound_ctrl:1
	v_mov_b32_dpp v153, v127 quad_perm:[1,0,3,2] row_mask:0xf bank_mask:0xf bound_ctrl:1
	v_mov_b32_dpp v154, v124 quad_perm:[1,0,3,2] row_mask:0xf bank_mask:0xf bound_ctrl:1
	v_mov_b32_dpp v155, v125 quad_perm:[1,0,3,2] row_mask:0xf bank_mask:0xf bound_ctrl:1
	v_mov_b32_dpp v156, v122 quad_perm:[1,0,3,2] row_mask:0xf bank_mask:0xf bound_ctrl:1
	v_mov_b32_dpp v157, v123 quad_perm:[1,0,3,2] row_mask:0xf bank_mask:0xf bound_ctrl:1
	v_mov_b32_dpp v158, v120 quad_perm:[1,0,3,2] row_mask:0xf bank_mask:0xf bound_ctrl:1
	v_mov_b32_dpp v141, v121 quad_perm:[1,0,3,2] row_mask:0xf bank_mask:0xf bound_ctrl:1
	v_mov_b32_dpp v159, v118 quad_perm:[1,0,3,2] row_mask:0xf bank_mask:0xf bound_ctrl:1
	v_mov_b32_dpp v160, v119 quad_perm:[1,0,3,2] row_mask:0xf bank_mask:0xf bound_ctrl:1
	s_and_saveexec_b64 s[30:31], vcc
	s_cbranch_execz .LBB0_980
	v_cvt_pk_bf16_f32 v160, v119, v160
	v_cvt_pk_bf16_f32 v159, v118, v159
	v_mad_u64_u32 v[118:119], s[46:47], v225, s83, v[116:117]
	v_cvt_pk_bf16_f32 v142, v142, v143
	v_lshl_add_u32 v118, v118, 1, s48
	ds_write_b32 v118, v142 offset:33792
	v_mad_u64_u32 v[118:119], s[46:47], v130, s85, v[116:117]
	v_lshl_add_u32 v118, v118, 1, s48
	v_cvt_pk_bf16_f32 v146, v146, v147
	v_cvt_pk_bf16_f32 v144, v144, v145
	v_add_u32_e32 v119, 0x8400, v118
	v_cvt_pk_bf16_f32 v121, v121, v141
	v_cvt_pk_bf16_f32 v126, v126, v152
	v_cvt_pk_bf16_f32 v141, v150, v151
	v_cvt_pk_bf16_f32 v129, v129, v149
	v_cvt_pk_bf16_f32 v128, v128, v148
	ds_write2_b32 v119, v144, v146 offset1:68
	ds_write2_b32 v119, v128, v129 offset0:136 offset1:204
	v_add_u32_e32 v119, 0x8800, v118
	v_cvt_pk_bf16_f32 v125, v125, v155
	v_cvt_pk_bf16_f32 v124, v124, v154
	v_cvt_pk_bf16_f32 v127, v127, v153
	ds_write2_b32 v119, v141, v126 offset0:16 offset1:84
	ds_write_b32 v118, v127 offset:35424
	v_add_u32_e32 v119, 0xa400, v118
	v_cvt_pk_bf16_f32 v123, v123, v157
	v_cvt_pk_bf16_f32 v122, v122, v156
	ds_write2_b32 v119, v124, v125 offset0:60 offset1:128
	v_add_u32_e32 v119, 0xa600, v118
	v_cvt_pk_bf16_f32 v120, v120, v158
	ds_write2_b32 v119, v122, v123 offset0:68 offset1:136
	v_add_u32_e32 v119, 0xa800, v118
	v_add_u32_e32 v118, 0xaa00, v118
	ds_write2_b32 v119, v120, v121 offset0:76 offset1:144
	ds_write2_b32 v118, v159, v160 offset0:84 offset1:152

; __device__ __forceinline__ void hgrn_h3(LAS unsigned char* lds, const bf16_t* Q, const _Float16* LF, const bf16_t* V, const bf16_t* SG, const bf16_t* SP, const float* gn, bf16_t* YAB, int cid, int G, int tid) {
;     ...
;         asm volatile("s_waitcnt lgkmcnt(0)" ::: "memory"); __syncthreads();
;         {   const int nx = h3_item(cid, G, grp, p + 1);
;             if (nx < NB * NH * NCH) { const int bh2 = nx >> 6, n2 = nx & 63; const size_t r2 = (size_t)(bh2 >> 3) * SEQ + (size_t)n2 * CH; const _Float16* lfc = LF + r2 * DH + (bh2 & 7) * 128; const bf16_t* vc = V + r2 * DH + (bh2 & 7) * 128;
.LBB0_983:
	s_waitcnt lgkmcnt(0)
	s_mov_b64 s[8:9], -1
	s_and_b64 vcc, exec, s[42:43]
	s_barrier
	s_cbranch_vccz .LBB0_985
	s_add_i32 s10, s63, s2
	s_mov_b64 s[8:9], 0

; #define PG8_STAGE(bufoff, gbase, voff) do { _Pragma("unroll") for (int _i = 0; _i < 2; ++_i) \
;         __builtin_amdgcn_global_load_lds((const unsigned*)((const char*)(gbase) + (voff)[_i]), (PG8_LAS unsigned*)(lds + (bufoff) + ldsw + _i * 8192), 16, 0, 0); } while (0)
; #define PG8_LDA(dst, b, h) do { _Pragma("unroll") for (int m = 0; m < 4; ++m) _Pragma("unroll") for (int k = 0; k < 2; ++k) dst[m][k] = *(const PG8_LAS bf16x8*)(lds + PG8_SA(b, h) + aoff + m * 2048 + k * 1024); } while (0)
; #define PG8_LDB(dst, b, h) do { _Pragma("unroll") for (int n = 0; n < 2; ++n) _Pragma("unroll") for (int k = 0; k < 2; ++k) dst[n][k] = *(const PG8_LAS bf16x8*)(lds + PG8_SB(b, h) + boff + n * 2048 + k * 1024); } while (0)
; #define PG8_WAIT_V(n) asm volatile("s_waitcnt vmcnt(" #n ")" ::: "memory")
; #define PG8_WAIT_L(n) asm volatile("s_waitcnt lgkmcnt(" #n ")" ::: "memory")
;     ...
;         for (int t = 0; t < nt; t += 2) {
;             const bool last = (t == nt - 2);
;             const char* a1 = cA + (ptrdiff_t)(t + 1) * kstepA;
;             const char* a2 = last ? nA : cA + (ptrdiff_t)(t + 2) * kstepA; const char* b2 = last ? nB : cB + (ptrdiff_t)(t + 2) * kstep;
;             const char* a3 = a2 + kstepA; const char* b3 = b2 + kstep;
;             if (last && has_next) S.a_ready(nxt);
;             if constexpr (SP2) {
;             PG8_LDB(B0, 0, 0); PG8_LDB(B1, 0, 1); PG8_SCHED; PG8_LDA(At, 0, 0); PG8_STAGE(PG8_SA(1, 1), a1 + hstepA, voffA);
;             PG8_WAIT_V(8); PG8_WAIT_L(0); PG8_BAR; PG8_MMA(0, 0, At, B0); PG8_MMA(0, 1, At, B1); PG8_BAR; PG8_SCHED;
;             PG8_LDA(At, 0, 1); PG8_STAGE(PG8_SB(0, 0), b2, voffB); PG8_STAGE(PG8_SB(0, 1), b2 + hstepB, voffB); PG8_STAGE(PG8_SA(0, 0), a2, voffA);
;             PG8_WAIT_V(8); PG8_WAIT_L(0); PG8_BAR; PG8_MMA(1, 0, At, B0); PG8_MMA(1, 1, At, B1); PG8_BAR; PG8_SCHED;
;             PG8_LDB(B0, 1, 0); PG8_LDB(B1, 1, 1); PG8_SCHED; PG8_LDA(At, 1, 0); PG8_STAGE(PG8_SA(0, 1), a2 + hstepA, voffA);
;             PG8_WAIT_V(8); PG8_WAIT_L(0); PG8_BAR; PG8_MMA(0, 0, At, B0); PG8_MMA(0, 1, At, B1); PG8_BAR; PG8_SCHED;
;             PG8_LDA(At, 1, 1); PG8_STAGE(PG8_SB(1, 0), b3, voffB); PG8_STAGE(PG8_SB(1, 1), b3 + hstepB, voffB); PG8_STAGE(PG8_SA(1, 0), a3, voffA);
;             PG8_WAIT_V(8); PG8_WAIT_L(0); PG8_BAR; PG8_MMA(1, 0, At, B0); PG8_MMA(1, 1, At, B1); PG8_BAR; PG8_SCHED;
.Ldn_nostg:
	s_or_b32 s44, s56, 1
	s_lshl_b64 s[34:35], s[44:45], 15
	s_sub_u32 s34, 0, s34
	s_subb_u32 s35, 0, s35
	s_add_u32 s44, s28, s34
	s_addc_u32 s65, s29, s35
	s_add_u32 s34, s30, 0xffff8000
	s_addc_u32 s35, s31, -1
	s_add_i32 s66, 0, 0x10000
	v_add_u32_e32 v0, s66, v230
	s_add_i32 s90, 0, 0x14000
	ds_read_b128 v[130:133], v0
	ds_read_b128 v[134:137], v0 offset:1024
	ds_read_b128 v[138:141], v0 offset:2048
	ds_read_b128 v[142:145], v0 offset:3072
	v_add_u32_e32 v0, s90, v230
	ds_read_b128 v[146:149], v0
	ds_read_b128 v[150:153], v0 offset:1024
	ds_read_b128 v[154:157], v0 offset:2048
	ds_read_b128 v[158:161], v0 offset:3072
	s_add_u32 s88, s44, 0x4000
	s_addc_u32 s89, s65, 0
	s_add_i32 m0, s46, 0xc000
	ds_read_b128 v[162:165], v231
	ds_read_b128 v[166:169], v231 offset:1024
	ds_read_b128 v[170:173], v231 offset:2048
	ds_read_b128 v[174:177], v231 offset:3072
	ds_read_b128 v[178:181], v231 offset:4096
	ds_read_b128 v[182:185], v231 offset:5120
	ds_read_b128 v[186:189], v231 offset:6144
	ds_read_b128 v[190:193], v231 offset:7168
	global_load_lds_dwordx4 v194, s[88:89]
	s_add_i32 m0, s46, 0xe000
	s_nop 0
	global_load_lds_dwordx4 v198, s[88:89]
	s_waitcnt vmcnt(8)
	s_waitcnt lgkmcnt(0)
	s_barrier
	s_setprio 1
	v_mfma_f32_16x16x32_bf16 v[126:129], v[130:133], v[162:165], 0
	v_mfma_f32_16x16x32_bf16 v[126:129], v[134:137], v[166:169], v[126:129]
	v_mfma_f32_16x16x32_bf16 v[122:125], v[142:145], v[166:169], 0
	v_mfma_f32_16x16x32_bf16 v[122:125], v[138:141], v[162:165], v[122:125]
	v_mfma_f32_16x16x32_bf16 v[106:109], v[138:141], v[170:173], 0
	v_mfma_f32_16x16x32_bf16 v[106:109], v[142:145], v[174:177], v[106:109]
	v_mfma_f32_16x16x32_bf16 v[110:113], v[134:137], v[174:177], 0
	v_mfma_f32_16x16x32_bf16 v[110:113], v[130:133], v[170:173], v[110:113]
	v_mfma_f32_16x16x32_bf16 v[94:97], v[130:133], v[178:181], 0
	v_mfma_f32_16x16x32_bf16 v[94:97], v[134:137], v[182:185], v[94:97]
	v_mfma_f32_16x16x32_bf16 v[90:93], v[142:145], v[182:185], 0
	v_mfma_f32_16x16x32_bf16 v[90:93], v[138:141], v[178:181], v[90:93]
	v_mfma_f32_16x16x32_bf16 v[74:77], v[138:141], v[186:189], 0
	v_mfma_f32_16x16x32_bf16 v[74:77], v[142:145], v[190:193], v[74:77]
	v_mfma_f32_16x16x32_bf16 v[78:81], v[134:137], v[190:193], 0
	v_mfma_f32_16x16x32_bf16 v[78:81], v[130:133], v[186:189], v[78:81]
	s_setprio 0
	s_setprio 1
	v_mfma_f32_16x16x32_bf16 v[118:121], v[146:149], v[162:165], 0
	v_mfma_f32_16x16x32_bf16 v[118:121], v[150:153], v[166:169], v[118:121]
	v_mfma_f32_16x16x32_bf16 v[114:117], v[158:161], v[166:169], 0
	v_mfma_f32_16x16x32_bf16 v[114:117], v[154:157], v[162:165], v[114:117]
	v_mfma_f32_16x16x32_bf16 v[98:101], v[154:157], v[170:173], 0
	v_mfma_f32_16x16x32_bf16 v[98:101], v[158:161], v[174:177], v[98:101]
	v_mfma_f32_16x16x32_bf16 v[102:105], v[150:153], v[174:177], 0
	v_mfma_f32_16x16x32_bf16 v[102:105], v[146:149], v[170:173], v[102:105]
	v_mfma_f32_16x16x32_bf16 v[86:89], v[146:149], v[178:181], 0
	v_mfma_f32_16x16x32_bf16 v[86:89], v[150:153], v[182:185], v[86:89]
	v_mfma_f32_16x16x32_bf16 v[82:85], v[158:161], v[182:185], 0
	v_mfma_f32_16x16x32_bf16 v[82:85], v[154:157], v[178:181], v[82:85]
	v_mfma_f32_16x16x32_bf16 v[66:69], v[154:157], v[186:189], 0
	v_mfma_f32_16x16x32_bf16 v[66:69], v[158:161], v[190:193], v[66:69]
	v_mfma_f32_16x16x32_bf16 v[70:73], v[150:153], v[190:193], 0
	v_mfma_f32_16x16x32_bf16 v[70:73], v[146:149], v[186:189], v[70:73]
	s_setprio 0
	s_barrier
	s_add_i32 s44, s66, s41
	s_mov_b32 m0, s44
	ds_read_b128 v[162:165], v231 offset:16384
	ds_read_b128 v[166:169], v231 offset:17408
	ds_read_b128 v[170:173], v231 offset:18432
	ds_read_b128 v[174:177], v231 offset:19456
	ds_read_b128 v[178:181], v231 offset:20480
	ds_read_b128 v[182:185], v231 offset:21504
	ds_read_b128 v[186:189], v231 offset:22528
	ds_read_b128 v[190:193], v231 offset:23552
	global_load_lds_dwordx4 v196, s[8:9]
	s_add_i32 m0, s44, 0x2000
	s_add_u32 s88, s8, 0x4000
	s_addc_u32 s89, s9, 0
	s_add_i32 s44, s90, s41
	global_load_lds_dwordx4 v200, s[8:9]
	s_mov_b32 m0, s44
	s_nop 0
	global_load_lds_dwordx4 v196, s[88:89]
	s_add_i32 m0, s44, 0x2000
	s_nop 0
	global_load_lds_dwordx4 v200, s[88:89]
	s_mov_b32 m0, s46
	s_nop 0
	global_load_lds_dwordx4 v194, s[30:31]
	s_mov_b32 m0, s47
	s_nop 0
	global_load_lds_dwordx4 v198, s[30:31]
	s_waitcnt vmcnt(8)
	s_waitcnt lgkmcnt(0)
	s_barrier
	s_setprio 1
	v_mfma_f32_16x16x32_bf16 v[62:65], v[130:133], v[162:165], 0
	v_mfma_f32_16x16x32_bf16 v[62:65], v[134:137], v[166:169], v[62:65]
	v_mfma_f32_16x16x32_bf16 v[58:61], v[142:145], v[166:169], 0
	v_mfma_f32_16x16x32_bf16 v[58:61], v[138:141], v[162:165], v[58:61]
	v_mfma_f32_16x16x32_bf16 v[42:45], v[138:141], v[170:173], 0
	v_mfma_f32_16x16x32_bf16 v[42:45], v[142:145], v[174:177], v[42:45]
	v_mfma_f32_16x16x32_bf16 v[46:49], v[134:137], v[174:177], 0
	v_mfma_f32_16x16x32_bf16 v[46:49], v[130:133], v[170:173], v[46:49]
	v_mfma_f32_16x16x32_bf16 v[30:33], v[130:133], v[178:181], 0
	v_mfma_f32_16x16x32_bf16 v[30:33], v[134:137], v[182:185], v[30:33]
	v_mfma_f32_16x16x32_bf16 v[26:29], v[142:145], v[182:185], 0
	v_mfma_f32_16x16x32_bf16 v[26:29], v[138:141], v[178:181], v[26:29]
	v_mfma_f32_16x16x32_bf16 v[10:13], v[138:141], v[186:189], 0
	v_mfma_f32_16x16x32_bf16 v[10:13], v[142:145], v[190:193], v[10:13]
	v_mfma_f32_16x16x32_bf16 v[14:17], v[134:137], v[190:193], 0
	v_mfma_f32_16x16x32_bf16 v[14:17], v[130:133], v[186:189], v[14:17]
	s_setprio 0
	s_setprio 1
	v_mfma_f32_16x16x32_bf16 v[54:57], v[146:149], v[162:165], 0
	v_mfma_f32_16x16x32_bf16 v[54:57], v[150:153], v[166:169], v[54:57]
	v_mfma_f32_16x16x32_bf16 v[50:53], v[158:161], v[166:169], 0
	v_mfma_f32_16x16x32_bf16 v[50:53], v[154:157], v[162:165], v[50:53]
	v_mfma_f32_16x16x32_bf16 v[34:37], v[154:157], v[170:173], 0
	v_mfma_f32_16x16x32_bf16 v[34:37], v[158:161], v[174:177], v[34:37]
	v_mfma_f32_16x16x32_bf16 v[38:41], v[150:153], v[174:177], 0
	v_mfma_f32_16x16x32_bf16 v[38:41], v[146:149], v[170:173], v[38:41]
	v_mfma_f32_16x16x32_bf16 v[22:25], v[146:149], v[178:181], 0
	v_mfma_f32_16x16x32_bf16 v[22:25], v[150:153], v[182:185], v[22:25]
	v_mfma_f32_16x16x32_bf16 v[18:21], v[158:161], v[182:185], 0
	v_mfma_f32_16x16x32_bf16 v[18:21], v[154:157], v[178:181], v[18:21]
	v_mfma_f32_16x16x32_bf16 v[2:5], v[154:157], v[186:189], 0
	v_mfma_f32_16x16x32_bf16 v[2:5], v[158:161], v[190:193], v[2:5]
	v_mfma_f32_16x16x32_bf16 v[6:9], v[150:153], v[190:193], 0
	v_mfma_f32_16x16x32_bf16 v[6:9], v[146:149], v[186:189], v[6:9]
	s_setprio 0
	s_barrier
	s_branch .Ldn_mid

; #define PG8_STAGE(bufoff, gbase, voff) do { _Pragma("unroll") for (int _i = 0; _i < 2; ++_i) \
;         __builtin_amdgcn_global_load_lds((const unsigned*)((const char*)(gbase) + (voff)[_i]), (PG8_LAS unsigned*)(lds + (bufoff) + ldsw + _i * 8192), 16, 0, 0); } while (0)
; #define PG8_LDA(dst, b, h) do { _Pragma("unroll") for (int m = 0; m < 4; ++m) _Pragma("unroll") for (int k = 0; k < 2; ++k) dst[m][k] = *(const PG8_LAS bf16x8*)(lds + PG8_SA(b, h) + aoff + m * 2048 + k * 1024); } while (0)
; #define PG8_LDB(dst, b, h) do { _Pragma("unroll") for (int n = 0; n < 2; ++n) _Pragma("unroll") for (int k = 0; k < 2; ++k) dst[n][k] = *(const PG8_LAS bf16x8*)(lds + PG8_SB(b, h) + boff + n * 2048 + k * 1024); } while (0)
; #define PG8_WAIT_V(n) asm volatile("s_waitcnt vmcnt(" #n ")" ::: "memory")
; #define PG8_WAIT_L(n) asm volatile("s_waitcnt lgkmcnt(" #n ")" ::: "memory")
;     ...
;         for (int t = 0; t < nt; t += 2) {
;             const bool last = (t == nt - 2);
;             const char* a1 = cA + (ptrdiff_t)(t + 1) * kstepA;
;             const char* a2 = last ? nA : cA + (ptrdiff_t)(t + 2) * kstepA; const char* b2 = last ? nB : cB + (ptrdiff_t)(t + 2) * kstep;
;             const char* a3 = a2 + kstepA; const char* b3 = b2 + kstep;
;             if (last && has_next) S.a_ready(nxt);
;             if constexpr (SP2) {
;             PG8_LDB(B0, 0, 0); PG8_LDB(B1, 0, 1); PG8_SCHED; PG8_LDA(At, 0, 0); PG8_STAGE(PG8_SA(1, 1), a1 + hstepA, voffA);
;             PG8_WAIT_V(8); PG8_WAIT_L(0); PG8_BAR; PG8_MMA(0, 0, At, B0); PG8_MMA(0, 1, At, B1); PG8_BAR; PG8_SCHED;
;             PG8_LDA(At, 0, 1); PG8_STAGE(PG8_SB(0, 0), b2, voffB); PG8_STAGE(PG8_SB(0, 1), b2 + hstepB, voffB); PG8_STAGE(PG8_SA(0, 0), a2, voffA);
;             PG8_WAIT_V(8); PG8_WAIT_L(0); PG8_BAR; PG8_MMA(1, 0, At, B0); PG8_MMA(1, 1, At, B1); PG8_BAR; PG8_SCHED;
;             PG8_LDB(B0, 1, 0); PG8_LDB(B1, 1, 1); PG8_SCHED; PG8_LDA(At, 1, 0); PG8_STAGE(PG8_SA(0, 1), a2 + hstepA, voffA);
;             PG8_WAIT_V(8); PG8_WAIT_L(0); PG8_BAR; PG8_MMA(0, 0, At, B0); PG8_MMA(0, 1, At, B1); PG8_BAR; PG8_SCHED;
;             PG8_LDA(At, 1, 1); PG8_STAGE(PG8_SB(1, 0), b3, voffB); PG8_STAGE(PG8_SB(1, 1), b3 + hstepB, voffB); PG8_STAGE(PG8_SA(1, 0), a3, voffA);
;             PG8_WAIT_V(8); PG8_WAIT_L(0); PG8_BAR; PG8_MMA(1, 0, At, B0); PG8_MMA(1, 1, At, B1); PG8_BAR; PG8_SCHED;
.LBB0_1444:
	s_or_b32 s44, s56, 1
	s_lshl_b64 s[34:35], s[44:45], 15
	s_sub_u32 s34, 0, s34
	s_subb_u32 s35, 0, s35
	s_add_u32 s44, s28, s34
	s_addc_u32 s65, s29, s35
	s_add_u32 s34, s30, 0xffff8000
	s_addc_u32 s35, s31, -1
	s_add_i32 s66, 0, 0x10000
	v_add_u32_e32 v0, s66, v230
	s_add_i32 s90, 0, 0x14000
	ds_read_b128 v[130:133], v0
	ds_read_b128 v[134:137], v0 offset:1024
	ds_read_b128 v[138:141], v0 offset:2048
	ds_read_b128 v[142:145], v0 offset:3072
	v_add_u32_e32 v0, s90, v230
	ds_read_b128 v[146:149], v0
	ds_read_b128 v[150:153], v0 offset:1024
	ds_read_b128 v[154:157], v0 offset:2048
	ds_read_b128 v[158:161], v0 offset:3072
	s_add_u32 s88, s44, 0x4000
	s_addc_u32 s89, s65, 0
	s_add_i32 m0, s46, 0xc000
	ds_read_b128 v[162:165], v231
	ds_read_b128 v[166:169], v231 offset:1024
	ds_read_b128 v[170:173], v231 offset:2048
	ds_read_b128 v[174:177], v231 offset:3072
	ds_read_b128 v[178:181], v231 offset:4096
	ds_read_b128 v[182:185], v231 offset:5120
	ds_read_b128 v[186:189], v231 offset:6144
	ds_read_b128 v[190:193], v231 offset:7168
	global_load_lds_dwordx4 v194, s[88:89]
	s_add_i32 m0, s46, 0xe000
	s_nop 0
	global_load_lds_dwordx4 v198, s[88:89]
	s_waitcnt vmcnt(8)
	s_waitcnt lgkmcnt(0)
	s_barrier
	s_setprio 1
	v_mfma_f32_16x16x32_bf16 v[126:129], v[130:133], v[162:165], v[126:129]
	v_mfma_f32_16x16x32_bf16 v[126:129], v[134:137], v[166:169], v[126:129]
	v_mfma_f32_16x16x32_bf16 v[122:125], v[142:145], v[166:169], v[122:125]
	v_mfma_f32_16x16x32_bf16 v[122:125], v[138:141], v[162:165], v[122:125]
	v_mfma_f32_16x16x32_bf16 v[106:109], v[138:141], v[170:173], v[106:109]
	v_mfma_f32_16x16x32_bf16 v[106:109], v[142:145], v[174:177], v[106:109]
	v_mfma_f32_16x16x32_bf16 v[110:113], v[134:137], v[174:177], v[110:113]
	v_mfma_f32_16x16x32_bf16 v[110:113], v[130:133], v[170:173], v[110:113]
	v_mfma_f32_16x16x32_bf16 v[94:97], v[130:133], v[178:181], v[94:97]
	v_mfma_f32_16x16x32_bf16 v[94:97], v[134:137], v[182:185], v[94:97]
	v_mfma_f32_16x16x32_bf16 v[90:93], v[142:145], v[182:185], v[90:93]
	v_mfma_f32_16x16x32_bf16 v[90:93], v[138:141], v[178:181], v[90:93]
	v_mfma_f32_16x16x32_bf16 v[74:77], v[138:141], v[186:189], v[74:77]
	v_mfma_f32_16x16x32_bf16 v[74:77], v[142:145], v[190:193], v[74:77]
	v_mfma_f32_16x16x32_bf16 v[78:81], v[134:137], v[190:193], v[78:81]
	v_mfma_f32_16x16x32_bf16 v[78:81], v[130:133], v[186:189], v[78:81]
	s_setprio 0
	s_setprio 1
	v_mfma_f32_16x16x32_bf16 v[118:121], v[146:149], v[162:165], v[118:121]
	v_mfma_f32_16x16x32_bf16 v[118:121], v[150:153], v[166:169], v[118:121]
	v_mfma_f32_16x16x32_bf16 v[114:117], v[158:161], v[166:169], v[114:117]
	v_mfma_f32_16x16x32_bf16 v[114:117], v[154:157], v[162:165], v[114:117]
	v_mfma_f32_16x16x32_bf16 v[98:101], v[154:157], v[170:173], v[98:101]
	v_mfma_f32_16x16x32_bf16 v[98:101], v[158:161], v[174:177], v[98:101]
	v_mfma_f32_16x16x32_bf16 v[102:105], v[150:153], v[174:177], v[102:105]
	v_mfma_f32_16x16x32_bf16 v[102:105], v[146:149], v[170:173], v[102:105]
	v_mfma_f32_16x16x32_bf16 v[86:89], v[146:149], v[178:181], v[86:89]
	v_mfma_f32_16x16x32_bf16 v[86:89], v[150:153], v[182:185], v[86:89]
	v_mfma_f32_16x16x32_bf16 v[82:85], v[158:161], v[182:185], v[82:85]
	v_mfma_f32_16x16x32_bf16 v[82:85], v[154:157], v[178:181], v[82:85]
	v_mfma_f32_16x16x32_bf16 v[66:69], v[154:157], v[186:189], v[66:69]
	v_mfma_f32_16x16x32_bf16 v[66:69], v[158:161], v[190:193], v[66:69]
	v_mfma_f32_16x16x32_bf16 v[70:73], v[150:153], v[190:193], v[70:73]
	v_mfma_f32_16x16x32_bf16 v[70:73], v[146:149], v[186:189], v[70:73]
	s_setprio 0
	s_barrier
	s_add_i32 s44, s66, s41
	s_mov_b32 m0, s44
	ds_read_b128 v[162:165], v231 offset:16384
	ds_read_b128 v[166:169], v231 offset:17408
	ds_read_b128 v[170:173], v231 offset:18432
	ds_read_b128 v[174:177], v231 offset:19456
	ds_read_b128 v[178:181], v231 offset:20480
	ds_read_b128 v[182:185], v231 offset:21504
	ds_read_b128 v[186:189], v231 offset:22528
	ds_read_b128 v[190:193], v231 offset:23552
	global_load_lds_dwordx4 v196, s[8:9]
	s_add_i32 m0, s44, 0x2000
	s_add_u32 s88, s8, 0x4000
	s_addc_u32 s89, s9, 0
	s_add_i32 s44, s90, s41
	global_load_lds_dwordx4 v200, s[8:9]
	s_mov_b32 m0, s44
	s_nop 0
	global_load_lds_dwordx4 v196, s[88:89]
	s_add_i32 m0, s44, 0x2000
	s_nop 0
	global_load_lds_dwordx4 v200, s[88:89]
	s_mov_b32 m0, s46
	s_nop 0
	global_load_lds_dwordx4 v194, s[30:31]
	s_mov_b32 m0, s47
	s_nop 0
	global_load_lds_dwordx4 v198, s[30:31]
	s_waitcnt vmcnt(8)
	s_waitcnt lgkmcnt(0)
	s_barrier
	s_setprio 1
	v_mfma_f32_16x16x32_bf16 v[62:65], v[130:133], v[162:165], v[62:65]
	v_mfma_f32_16x16x32_bf16 v[62:65], v[134:137], v[166:169], v[62:65]
	v_mfma_f32_16x16x32_bf16 v[58:61], v[142:145], v[166:169], v[58:61]
	v_mfma_f32_16x16x32_bf16 v[58:61], v[138:141], v[162:165], v[58:61]
	v_mfma_f32_16x16x32_bf16 v[42:45], v[138:141], v[170:173], v[42:45]
	v_mfma_f32_16x16x32_bf16 v[42:45], v[142:145], v[174:177], v[42:45]
	v_mfma_f32_16x16x32_bf16 v[46:49], v[134:137], v[174:177], v[46:49]
	v_mfma_f32_16x16x32_bf16 v[46:49], v[130:133], v[170:173], v[46:49]
	v_mfma_f32_16x16x32_bf16 v[30:33], v[130:133], v[178:181], v[30:33]
	v_mfma_f32_16x16x32_bf16 v[30:33], v[134:137], v[182:185], v[30:33]
	v_mfma_f32_16x16x32_bf16 v[26:29], v[142:145], v[182:185], v[26:29]
	v_mfma_f32_16x16x32_bf16 v[26:29], v[138:141], v[178:181], v[26:29]
	v_mfma_f32_16x16x32_bf16 v[10:13], v[138:141], v[186:189], v[10:13]
	v_mfma_f32_16x16x32_bf16 v[10:13], v[142:145], v[190:193], v[10:13]
	v_mfma_f32_16x16x32_bf16 v[14:17], v[134:137], v[190:193], v[14:17]
	v_mfma_f32_16x16x32_bf16 v[14:17], v[130:133], v[186:189], v[14:17]
	s_setprio 0
	s_setprio 1
	v_mfma_f32_16x16x32_bf16 v[54:57], v[146:149], v[162:165], v[54:57]
	v_mfma_f32_16x16x32_bf16 v[54:57], v[150:153], v[166:169], v[54:57]
	v_mfma_f32_16x16x32_bf16 v[50:53], v[158:161], v[166:169], v[50:53]
	v_mfma_f32_16x16x32_bf16 v[50:53], v[154:157], v[162:165], v[50:53]
	v_mfma_f32_16x16x32_bf16 v[34:37], v[154:157], v[170:173], v[34:37]
	v_mfma_f32_16x16x32_bf16 v[34:37], v[158:161], v[174:177], v[34:37]
	v_mfma_f32_16x16x32_bf16 v[38:41], v[150:153], v[174:177], v[38:41]
	v_mfma_f32_16x16x32_bf16 v[38:41], v[146:149], v[170:173], v[38:41]
	v_mfma_f32_16x16x32_bf16 v[22:25], v[146:149], v[178:181], v[22:25]
	v_mfma_f32_16x16x32_bf16 v[22:25], v[150:153], v[182:185], v[22:25]
	v_mfma_f32_16x16x32_bf16 v[18:21], v[158:161], v[182:185], v[18:21]
	v_mfma_f32_16x16x32_bf16 v[18:21], v[154:157], v[178:181], v[18:21]
	v_mfma_f32_16x16x32_bf16 v[2:5], v[154:157], v[186:189], v[2:5]
	v_mfma_f32_16x16x32_bf16 v[2:5], v[158:161], v[190:193], v[2:5]
	v_mfma_f32_16x16x32_bf16 v[6:9], v[150:153], v[190:193], v[6:9]
	v_mfma_f32_16x16x32_bf16 v[6:9], v[146:149], v[186:189], v[6:9]
	s_setprio 0
	s_barrier
